# hand-written P4 mix-prep (row loads batched + next-row prefetch) and dn_prep S1 conv/silu/l2norm (all loads of a part issued together)
# speedup vs baseline: 1.1134x; 1.0193x over previous
; DI void dn_prep(const Params& p, int item, char* smem) {
;     ...
;   for (int ps = 0; ps < 8; ++ps) {
;     const int combo = ps * 16 + (tid >> 4);
;     const int tt = combo & 63, part = combo >> 6, sub = tid & 15;
;     const int col = part * 512 + h * 128 + sub * 8;
;     float y[8] = {0.f, 0.f, 0.f, 0.f, 0.f, 0.f, 0.f, 0.f};
; #pragma unroll
;     for (int j = 0; j < 4; ++j) {
;       const int t = t0 + tt - 3 + j;
;       if (t >= 0) {
;         uint4 xv = *(const uint4*)&p.proj[(rowbase + t) * NP + col];
;         float4 wa = *(const float4*)&p.conv_w[j * 1536 + col], wb = *(const float4*)&p.conv_w[j * 1536 + col + 4];
.LBB0_373:
	s_or_b64 exec, exec, s[0:1]
	s_and_b32 s3, s2, 0x180
	v_add_u32_e32 v3, s3, v215
	s_and_b32 s6, s61, 0x1fc0
	v_or_b32_e32 v8, s6, v212
	v_lshlrev_b32_e32 v6, 1, v3
	v_mov_b32_e32 v7, v0
	v_or_b32_e32 v12, s3, v204
	v_lshlrev_b32_e32 v4, 2, v3
	v_mad_u64_u32 v[16:17], s[0:1], v8, s63, v[6:7]
	v_or_b32_e32 v3, s6, v197
	v_lshlrev_b32_e32 v8, 1, v12
	v_mov_b32_e32 v9, v0
	v_mad_u64_u32 v[18:19], s[0:1], v3, s63, v[8:9]
	v_add_u32_e32 v3, -1, v197
	v_add_u32_e32 v3, s6, v3
	v_mad_u64_u32 v[20:21], s[0:1], v3, s63, v[8:9]
	v_add_u32_e32 v3, -2, v197
	v_add_u32_e32 v3, s6, v3
	v_mad_u64_u32 v[22:23], s[0:1], v3, s63, v[8:9]
	v_add_u32_e32 v3, -1, v212
	v_add_u32_e32 v3, s6, v3
	v_mad_u64_u32 v[24:25], s[0:1], v3, s63, v[6:7]
	v_add_u32_e32 v3, -3, v197
	v_add_u32_e32 v3, s6, v3
	v_mad_u64_u32 v[26:27], s[0:1], v3, s63, v[8:9]
	v_add_u32_e32 v3, -2, v212
	v_add_u32_e32 v3, s6, v3
	v_mad_u64_u32 v[28:29], s[0:1], v3, s63, v[6:7]
	v_add_u32_e32 v3, -3, v212
	v_add_u32_e32 v3, s6, v3
	v_mad_u64_u32 v[30:31], s[0:1], v3, s63, v[6:7]
	v_add_u32_e32 v3, s3, v216
	v_lshlrev_b32_e32 v8, 2, v12
	v_lshlrev_b32_e32 v6, 2, v3
	v_lshlrev_b32_e32 v12, 1, v3
	v_add_u32_e32 v3, -1, v210
	v_mov_b32_e32 v13, v0
	v_add_u32_e32 v3, s6, v3
	v_mad_u64_u32 v[34:35], s[0:1], v3, s63, v[12:13]
	v_add_u32_e32 v3, -2, v210
	v_add_u32_e32 v3, s6, v3
	v_mad_u64_u32 v[36:37], s[0:1], v3, s63, v[12:13]
	v_add_u32_e32 v3, -3, v210
	v_add_u32_e32 v3, s6, v3
	v_or_b32_e32 v14, s6, v210
	v_mad_u64_u32 v[38:39], s[0:1], v3, s63, v[12:13]
	v_add_u32_e32 v3, s3, v217
	v_mad_u64_u32 v[32:33], s[0:1], v14, s63, v[12:13]
	v_lshlrev_b32_e32 v12, 2, v3
	v_lshlrev_b32_e32 v14, 1, v3
	v_add_u32_e32 v3, -3, v209
	v_mov_b32_e32 v15, v0
	v_add_u32_e32 v3, s6, v3
	v_mad_u64_u32 v[42:43], s[0:1], v3, s63, v[14:15]
	v_add_u32_e32 v3, -2, v209
	v_add_u32_e32 v3, s6, v3
	v_mad_u64_u32 v[44:45], s[0:1], v3, s63, v[14:15]
	v_add_u32_e32 v3, -1, v209
	v_add_u32_e32 v3, s6, v3
	v_mad_u64_u32 v[46:47], s[0:1], v3, s63, v[14:15]
	v_xor_b32_e32 v3, 1, v1
	v_add_u32_e32 v2, 64, v2
	v_cmp_lt_i32_e32 vcc, v3, v2
	v_or_b32_e32 v40, s6, v209
	v_mad_u64_u32 v[40:41], s[0:1], v40, s63, v[14:15]
	v_cndmask_b32_e32 v3, v1, v3, vcc
	v_lshlrev_b32_e32 v61, 2, v3
	v_xor_b32_e32 v3, 2, v1
	v_cmp_lt_i32_e32 vcc, v3, v2
	s_add_i32 s3, s46, -3
	ds_read_b64 v[14:15], v222
	ds_read_b64 v[56:57], v223
	v_cndmask_b32_e32 v3, v1, v3, vcc
	v_lshlrev_b32_e32 v71, 2, v3
	v_xor_b32_e32 v3, 4, v1
	v_cmp_lt_i32_e32 vcc, v3, v2
	v_mov_b32_e32 v5, v0
	s_mul_hi_i32 s31, s30, 0x4400000
	v_cndmask_b32_e32 v3, v1, v3, vcc
	v_lshlrev_b32_e32 v73, 2, v3
	v_xor_b32_e32 v3, 8, v1
	v_cmp_lt_i32_e32 vcc, v3, v2
	s_mul_i32 s30, s30, 0x4400000
	s_waitcnt lgkmcnt(0)
	v_lshl_add_u64 v[48:49], v[56:57], 0, v[4:5]
	v_cndmask_b32_e32 v1, v1, v3, vcc
	v_lshlrev_b32_e32 v80, 2, v1
	v_add_u32_e32 v1, s3, v197
	v_cmp_lt_i32_e64 s[90:91], -1, v1
	v_cmp_lt_i32_e64 s[92:93], -2, v1
	v_cmp_lt_i32_e64 s[94:95], -3, v1
	v_add_u32_e32 v1, s3, v209
	v_cmp_lt_i32_e64 s[96:97], -1, v1
	v_cmp_lt_i32_e64 s[0:1], -2, v1
	v_cmp_lt_i32_e64 s[6:7], -3, v1
	v_add_u32_e32 v1, s3, v210
	v_cmp_lt_i32_e64 s[16:17], -1, v1
	v_cmp_lt_i32_e64 s[18:19], -2, v1
	v_cmp_lt_i32_e64 s[20:21], -3, v1
	v_add_u32_e32 v1, s3, v212
	v_cmp_lt_i32_e64 s[22:23], -1, v1
	v_cmp_lt_i32_e64 s[24:25], -2, v1
	v_cmp_lt_i32_e64 s[14:15], -3, v1
	v_lshl_add_u64 v[50:51], v[14:15], 0, s[30:31]
	v_lshl_add_u64 v[52:53], v[56:57], 0, v[8:9]
	v_lshl_add_u64 v[54:55], v[56:57], 0, v[6:7]
	v_lshl_add_u64 v[56:57], v[56:57], 0, v[12:13]
	s_mov_b64 s[30:31], 0
	v_mov_b32_e32 v81, v211
	s_lshr_b32 s31, s2, 7
	s_and_b32 s30, s31, 3
	s_lshr_b32 s31, s31, 2
	s_lshl_b32 s31, s31, 13
	s_and_b32 s34, s2, 0x7f
	s_lshl_b32 s34, s34, 6
	s_add_i32 s31, s31, s34
	s_add_i32 s31, s31, -3
	s_mul_i32 s31, s31, 0x2200
	v_lshrrev_b32_e32 v195, 4, v142
	v_and_b32_e32 v194, 15, v142
	v_mul_u32_u24_e32 v195, 0x2200, v195
	v_lshl_add_u32 v195, v194, 4, v195
	v_lshlrev_b32_e32 v94, 5, v194
	v_mov_b32_e32 v90, 0x10160
	v_mov_b32_e32 v92, 0x10058
	ds_read_b64 v[96:97], v90
	ds_read_b64 v[100:101], v92
	s_waitcnt lgkmcnt(0)
	v_readfirstlane_b32 s98, v96
	v_readfirstlane_b32 s99, v97
	v_readfirstlane_b32 s100, v100
	v_readfirstlane_b32 s101, v101
	s_lshl_b32 s34, s30, 8
	s_add_i32 s34, s34, s31
	s_ashr_i32 s35, s34, 31
	s_add_u32 s98, s98, s34
	s_addc_u32 s99, s99, s35
	s_lshl_b32 s34, s30, 9
	s_add_u32 s100, s100, s34
	s_addc_u32 s101, s101, 0
	s_nop 1
	global_load_dwordx4 v[96:99], v195, s[98:99]
	s_add_u32 s98, s98, 0x2200
	s_addc_u32 s99, s99, 0
	global_load_dwordx4 v[100:103], v195, s[98:99]
	s_add_u32 s98, s98, 0x2200
	s_addc_u32 s99, s99, 0
	global_load_dwordx4 v[104:107], v195, s[98:99]
	s_add_u32 s98, s98, 0x2200
	s_addc_u32 s99, s99, 0
	global_load_dwordx4 v[108:111], v195, s[98:99]
	s_add_u32 s98, s98, 0x1ba00
	s_addc_u32 s99, s99, 0
	global_load_dwordx4 v[112:115], v195, s[98:99]
	s_add_u32 s98, s98, 0x2200
	s_addc_u32 s99, s99, 0
	global_load_dwordx4 v[116:119], v195, s[98:99]
	s_add_u32 s98, s98, 0x2200
	s_addc_u32 s99, s99, 0
	global_load_dwordx4 v[120:123], v195, s[98:99]
	s_add_u32 s98, s98, 0x2200
	s_addc_u32 s99, s99, 0
	global_load_dwordx4 v[124:127], v195, s[98:99]
	s_add_u32 s98, s98, 0x1ba00
	s_addc_u32 s99, s99, 0
	global_load_dwordx4 v[12:15], v195, s[98:99]
	s_add_u32 s98, s98, 0x2200
	s_addc_u32 s99, s99, 0
	global_load_dwordx4 v[16:19], v195, s[98:99]
	s_add_u32 s98, s98, 0x2200
	s_addc_u32 s99, s99, 0
	global_load_dwordx4 v[20:23], v195, s[98:99]
	s_add_u32 s98, s98, 0x2200
	s_addc_u32 s99, s99, 0
	global_load_dwordx4 v[24:27], v195, s[98:99]
	s_add_u32 s98, s98, 0x1ba00
	s_addc_u32 s99, s99, 0
	global_load_dwordx4 v[28:31], v195, s[98:99]
	s_add_u32 s98, s98, 0x2200
	s_addc_u32 s99, s99, 0
	global_load_dwordx4 v[32:35], v195, s[98:99]
	s_add_u32 s98, s98, 0x2200
	s_addc_u32 s99, s99, 0
	global_load_dwordx4 v[36:39], v195, s[98:99]
	s_add_u32 s98, s98, 0x2200
	s_addc_u32 s99, s99, 0
	global_load_dwordx4 v[40:43], v195, s[98:99]
	global_load_dwordx4 v[152:155], v94, s[100:101]
	global_load_dwordx4 v[156:159], v94, s[100:101] offset:16
	s_add_u32 s100, s100, 0x1800
	s_addc_u32 s101, s101, 0
	global_load_dwordx4 v[160:163], v94, s[100:101]
	global_load_dwordx4 v[164:167], v94, s[100:101] offset:16
	s_add_u32 s100, s100, 0x1800
	s_addc_u32 s101, s101, 0
	global_load_dwordx4 v[168:171], v94, s[100:101]
	global_load_dwordx4 v[44:47], v94, s[100:101] offset:16
	s_add_u32 s100, s100, 0x1800
	s_addc_u32 s101, s101, 0
	global_load_dwordx4 v[48:51], v94, s[100:101]
	global_load_dwordx4 v[128:131], v94, s[100:101] offset:16
	s_waitcnt vmcnt(0)
	s_and_b32 s34, s2, 0x7f
	s_cmp_lg_u32 s34, 0
	s_cbranch_scc1 .Ls1_nomask0
; DI float bflo(unsigned d) { return __uint_as_float(d << 16); }
; DI float bfhi(unsigned d) { return __uint_as_float(d & 0xffff0000u); }
; DI void dn_prep(const Params& p, int item, char* smem) {
;     ...
; #pragma unroll
;     for (int j = 0; j < 4; ++j) {
;       const int t = t0 + tt - 3 + j;
;       if (t >= 0) {
;         uint4 xv = *(const uint4*)&p.proj[(rowbase + t) * NP + col];
;         float4 wa = *(const float4*)&p.conv_w[j * 1536 + col], wb = *(const float4*)&p.conv_w[j * 1536 + col + 4];
;         y[0] += bflo(xv.x) * wa.x; y[1] += bfhi(xv.x) * wa.y; y[2] += bflo(xv.y) * wa.z; y[3] += bfhi(xv.y) * wa.w;
;         y[4] += bflo(xv.z) * wb.x; y[5] += bfhi(xv.z) * wb.y; y[6] += bflo(xv.w) * wb.z; y[7] += bfhi(xv.w) * wb.w;
	v_lshrrev_b32_e32 v90, 4, v142
	v_cmp_gt_u32_e32 vcc, 3, v90
	s_nop 1
	v_cndmask_b32_e64 v96, v96, 0, vcc
	v_cndmask_b32_e64 v97, v97, 0, vcc
	v_cndmask_b32_e64 v98, v98, 0, vcc
	v_cndmask_b32_e64 v99, v99, 0, vcc
	v_cmp_gt_u32_e32 vcc, 2, v90
	s_nop 1
	v_cndmask_b32_e64 v100, v100, 0, vcc
	v_cndmask_b32_e64 v101, v101, 0, vcc
	v_cndmask_b32_e64 v102, v102, 0, vcc
	v_cndmask_b32_e64 v103, v103, 0, vcc
	v_cmp_gt_u32_e32 vcc, 1, v90
	s_nop 1
	v_cndmask_b32_e64 v104, v104, 0, vcc
	v_cndmask_b32_e64 v105, v105, 0, vcc
	v_cndmask_b32_e64 v106, v106, 0, vcc
	v_cndmask_b32_e64 v107, v107, 0, vcc
.Ls1_nomask0:
	v_lshlrev_b32_e32 v90, 16, v96
	v_and_b32_e32 v92, 0xffff0000, v96
	v_mul_f32_e32 v1, v90, v152
	v_mul_f32_e32 v2, v92, v153
	v_lshlrev_b32_e32 v90, 16, v97
	v_and_b32_e32 v92, 0xffff0000, v97
	v_mul_f32_e32 v3, v90, v154
	v_mul_f32_e32 v4, v92, v155
	v_lshlrev_b32_e32 v90, 16, v98
	v_and_b32_e32 v92, 0xffff0000, v98
	v_mul_f32_e32 v5, v90, v156
	v_mul_f32_e32 v6, v92, v157
	v_lshlrev_b32_e32 v90, 16, v99
	v_and_b32_e32 v92, 0xffff0000, v99
	v_mul_f32_e32 v7, v90, v158
	v_mul_f32_e32 v8, v92, v159
	v_lshlrev_b32_e32 v90, 16, v100
	v_and_b32_e32 v92, 0xffff0000, v100
	v_fmac_f32_e32 v1, v90, v160
	v_fmac_f32_e32 v2, v92, v161
	v_lshlrev_b32_e32 v90, 16, v101
	v_and_b32_e32 v92, 0xffff0000, v101
	v_fmac_f32_e32 v3, v90, v162
	v_fmac_f32_e32 v4, v92, v163
	v_lshlrev_b32_e32 v90, 16, v102
	v_and_b32_e32 v92, 0xffff0000, v102
	v_fmac_f32_e32 v5, v90, v164
	v_fmac_f32_e32 v6, v92, v165
	v_lshlrev_b32_e32 v90, 16, v103
	v_and_b32_e32 v92, 0xffff0000, v103
	v_fmac_f32_e32 v7, v90, v166
	v_fmac_f32_e32 v8, v92, v167
	v_lshlrev_b32_e32 v90, 16, v104
	v_and_b32_e32 v92, 0xffff0000, v104
	v_fmac_f32_e32 v1, v90, v168
	v_fmac_f32_e32 v2, v92, v169
	v_lshlrev_b32_e32 v90, 16, v105
	v_and_b32_e32 v92, 0xffff0000, v105
	v_fmac_f32_e32 v3, v90, v170
	v_fmac_f32_e32 v4, v92, v171
	v_lshlrev_b32_e32 v90, 16, v106
	v_and_b32_e32 v92, 0xffff0000, v106
	v_fmac_f32_e32 v5, v90, v44
	v_fmac_f32_e32 v6, v92, v45
	v_lshlrev_b32_e32 v90, 16, v107
	v_and_b32_e32 v92, 0xffff0000, v107
	v_fmac_f32_e32 v7, v90, v46
	v_fmac_f32_e32 v8, v92, v47
	v_lshlrev_b32_e32 v90, 16, v108
	v_and_b32_e32 v92, 0xffff0000, v108
	v_fmac_f32_e32 v1, v90, v48
	v_fmac_f32_e32 v2, v92, v49
	v_lshlrev_b32_e32 v90, 16, v109
	v_and_b32_e32 v92, 0xffff0000, v109
	v_fmac_f32_e32 v3, v90, v50
	v_fmac_f32_e32 v4, v92, v51
	v_lshlrev_b32_e32 v90, 16, v110
	v_and_b32_e32 v92, 0xffff0000, v110
	v_fmac_f32_e32 v5, v90, v128
	v_fmac_f32_e32 v6, v92, v129
	v_lshlrev_b32_e32 v90, 16, v111
	v_and_b32_e32 v92, 0xffff0000, v111
	v_fmac_f32_e32 v7, v90, v130
	v_fmac_f32_e32 v8, v92, v131
	v_lshlrev_b32_e32 v90, 16, v112
	v_and_b32_e32 v92, 0xffff0000, v112
	v_mul_f32_e32 v9, v90, v152
	v_mul_f32_e32 v240, v92, v153
	v_lshlrev_b32_e32 v90, 16, v113
	v_and_b32_e32 v92, 0xffff0000, v113
	v_mul_f32_e32 v241, v90, v154
	v_mul_f32_e32 v242, v92, v155
	v_lshlrev_b32_e32 v90, 16, v114
	v_and_b32_e32 v92, 0xffff0000, v114
	v_mul_f32_e32 v243, v90, v156
	v_mul_f32_e32 v244, v92, v157
	v_lshlrev_b32_e32 v90, 16, v115
	v_and_b32_e32 v92, 0xffff0000, v115
	v_mul_f32_e32 v245, v90, v158
	v_mul_f32_e32 v246, v92, v159
	v_lshlrev_b32_e32 v90, 16, v116
	v_and_b32_e32 v92, 0xffff0000, v116
	v_fmac_f32_e32 v9, v90, v160
	v_fmac_f32_e32 v240, v92, v161
	v_lshlrev_b32_e32 v90, 16, v117
	v_and_b32_e32 v92, 0xffff0000, v117
	v_fmac_f32_e32 v241, v90, v162
	v_fmac_f32_e32 v242, v92, v163
	v_lshlrev_b32_e32 v90, 16, v118
	v_and_b32_e32 v92, 0xffff0000, v118
	v_fmac_f32_e32 v243, v90, v164
	v_fmac_f32_e32 v244, v92, v165
	v_lshlrev_b32_e32 v90, 16, v119
	v_and_b32_e32 v92, 0xffff0000, v119
	v_fmac_f32_e32 v245, v90, v166
	v_fmac_f32_e32 v246, v92, v167
	v_lshlrev_b32_e32 v90, 16, v120
	v_and_b32_e32 v92, 0xffff0000, v120
	v_fmac_f32_e32 v9, v90, v168
	v_fmac_f32_e32 v240, v92, v169
	v_lshlrev_b32_e32 v90, 16, v121
	v_and_b32_e32 v92, 0xffff0000, v121
	v_fmac_f32_e32 v241, v90, v170
	v_fmac_f32_e32 v242, v92, v171
	v_lshlrev_b32_e32 v90, 16, v122
	v_and_b32_e32 v92, 0xffff0000, v122
	v_fmac_f32_e32 v243, v90, v44
	v_fmac_f32_e32 v244, v92, v45
	v_lshlrev_b32_e32 v90, 16, v123
	v_and_b32_e32 v92, 0xffff0000, v123
	v_fmac_f32_e32 v245, v90, v46
	v_fmac_f32_e32 v246, v92, v47
	v_lshlrev_b32_e32 v90, 16, v124
	v_and_b32_e32 v92, 0xffff0000, v124
	v_fmac_f32_e32 v9, v90, v48
	v_fmac_f32_e32 v240, v92, v49
	v_lshlrev_b32_e32 v90, 16, v125
	v_and_b32_e32 v92, 0xffff0000, v125
	v_fmac_f32_e32 v241, v90, v50
	v_fmac_f32_e32 v242, v92, v51
	v_lshlrev_b32_e32 v90, 16, v126
	v_and_b32_e32 v92, 0xffff0000, v126
	v_fmac_f32_e32 v243, v90, v128
	v_fmac_f32_e32 v244, v92, v129
	v_lshlrev_b32_e32 v90, 16, v127
	v_and_b32_e32 v92, 0xffff0000, v127
	v_fmac_f32_e32 v245, v90, v130
	v_fmac_f32_e32 v246, v92, v131
	v_lshlrev_b32_e32 v90, 16, v12
	v_and_b32_e32 v92, 0xffff0000, v12
	v_mul_f32_e32 v247, v90, v152
	v_mul_f32_e32 v248, v92, v153
	v_lshlrev_b32_e32 v90, 16, v13
	v_and_b32_e32 v92, 0xffff0000, v13
	v_mul_f32_e32 v249, v90, v154
	v_mul_f32_e32 v250, v92, v155
	v_lshlrev_b32_e32 v90, 16, v14
	v_and_b32_e32 v92, 0xffff0000, v14
	v_mul_f32_e32 v251, v90, v156
	v_mul_f32_e32 v252, v92, v157
	v_lshlrev_b32_e32 v90, 16, v15
	v_and_b32_e32 v92, 0xffff0000, v15
	v_mul_f32_e32 v253, v90, v158
	v_mul_f32_e32 v254, v92, v159
	v_lshlrev_b32_e32 v90, 16, v16
	v_and_b32_e32 v92, 0xffff0000, v16
	v_fmac_f32_e32 v247, v90, v160
	v_fmac_f32_e32 v248, v92, v161
	v_lshlrev_b32_e32 v90, 16, v17
	v_and_b32_e32 v92, 0xffff0000, v17
	v_fmac_f32_e32 v249, v90, v162
	v_fmac_f32_e32 v250, v92, v163
	v_lshlrev_b32_e32 v90, 16, v18
	v_and_b32_e32 v92, 0xffff0000, v18
; DI float bflo(unsigned d) { return __uint_as_float(d << 16); }
; DI float bfhi(unsigned d) { return __uint_as_float(d & 0xffff0000u); }
; DI float siluf(float x) { return x / (1.f + __expf(-x)); }
; DI void dn_prep(const Params& p, int item, char* smem) {
;     ...
;         y[0] += bflo(xv.x) * wa.x; y[1] += bfhi(xv.x) * wa.y; y[2] += bflo(xv.y) * wa.z; y[3] += bfhi(xv.y) * wa.w;
;         y[4] += bflo(xv.z) * wb.x; y[5] += bfhi(xv.z) * wb.y; y[6] += bflo(xv.w) * wb.z; y[7] += bfhi(xv.w) * wb.w;
;       }
;     }
;     float ss = 0.f;
; #pragma unroll
;     for (int e = 0; e < 8; ++e) { y[e] = siluf(y[e]); ss += y[e] * y[e]; }
	v_fmac_f32_e32 v251, v90, v164
	v_fmac_f32_e32 v252, v92, v165
	v_lshlrev_b32_e32 v90, 16, v19
	v_and_b32_e32 v92, 0xffff0000, v19
	v_fmac_f32_e32 v253, v90, v166
	v_fmac_f32_e32 v254, v92, v167
	v_lshlrev_b32_e32 v90, 16, v20
	v_and_b32_e32 v92, 0xffff0000, v20
	v_fmac_f32_e32 v247, v90, v168
	v_fmac_f32_e32 v248, v92, v169
	v_lshlrev_b32_e32 v90, 16, v21
	v_and_b32_e32 v92, 0xffff0000, v21
	v_fmac_f32_e32 v249, v90, v170
	v_fmac_f32_e32 v250, v92, v171
	v_lshlrev_b32_e32 v90, 16, v22
	v_and_b32_e32 v92, 0xffff0000, v22
	v_fmac_f32_e32 v251, v90, v44
	v_fmac_f32_e32 v252, v92, v45
	v_lshlrev_b32_e32 v90, 16, v23
	v_and_b32_e32 v92, 0xffff0000, v23
	v_fmac_f32_e32 v253, v90, v46
	v_fmac_f32_e32 v254, v92, v47
	v_lshlrev_b32_e32 v90, 16, v24
	v_and_b32_e32 v92, 0xffff0000, v24
	v_fmac_f32_e32 v247, v90, v48
	v_fmac_f32_e32 v248, v92, v49
	v_lshlrev_b32_e32 v90, 16, v25
	v_and_b32_e32 v92, 0xffff0000, v25
	v_fmac_f32_e32 v249, v90, v50
	v_fmac_f32_e32 v250, v92, v51
	v_lshlrev_b32_e32 v90, 16, v26
	v_and_b32_e32 v92, 0xffff0000, v26
	v_fmac_f32_e32 v251, v90, v128
	v_fmac_f32_e32 v252, v92, v129
	v_lshlrev_b32_e32 v90, 16, v27
	v_and_b32_e32 v92, 0xffff0000, v27
	v_fmac_f32_e32 v253, v90, v130
	v_fmac_f32_e32 v254, v92, v131
	v_lshlrev_b32_e32 v96, 16, v28
	v_and_b32_e32 v97, 0xffff0000, v28
	v_mul_f32_e32 v61, v96, v152
	v_mul_f32_e32 v71, v97, v153
	v_lshlrev_b32_e32 v96, 16, v29
	v_and_b32_e32 v97, 0xffff0000, v29
	v_mul_f32_e32 v73, v96, v154
	v_mul_f32_e32 v88, v97, v155
	v_lshlrev_b32_e32 v96, 16, v30
	v_and_b32_e32 v97, 0xffff0000, v30
	v_mul_f32_e32 v90, v96, v156
	v_mul_f32_e32 v92, v97, v157
	v_lshlrev_b32_e32 v96, 16, v31
	v_and_b32_e32 v97, 0xffff0000, v31
	v_mul_f32_e32 v94, v96, v158
	v_mul_f32_e32 v194, v97, v159
	v_lshlrev_b32_e32 v96, 16, v32
	v_and_b32_e32 v97, 0xffff0000, v32
	v_fmac_f32_e32 v61, v96, v160
	v_fmac_f32_e32 v71, v97, v161
	v_lshlrev_b32_e32 v96, 16, v33
	v_and_b32_e32 v97, 0xffff0000, v33
	v_fmac_f32_e32 v73, v96, v162
	v_fmac_f32_e32 v88, v97, v163
	v_lshlrev_b32_e32 v96, 16, v34
	v_and_b32_e32 v97, 0xffff0000, v34
	v_fmac_f32_e32 v90, v96, v164
	v_fmac_f32_e32 v92, v97, v165
	v_lshlrev_b32_e32 v96, 16, v35
	v_and_b32_e32 v97, 0xffff0000, v35
	v_fmac_f32_e32 v94, v96, v166
	v_fmac_f32_e32 v194, v97, v167
	v_lshlrev_b32_e32 v96, 16, v36
	v_and_b32_e32 v97, 0xffff0000, v36
	v_fmac_f32_e32 v61, v96, v168
	v_fmac_f32_e32 v71, v97, v169
	v_lshlrev_b32_e32 v96, 16, v37
	v_and_b32_e32 v97, 0xffff0000, v37
	v_fmac_f32_e32 v73, v96, v170
	v_fmac_f32_e32 v88, v97, v171
	v_lshlrev_b32_e32 v96, 16, v38
	v_and_b32_e32 v97, 0xffff0000, v38
	v_fmac_f32_e32 v90, v96, v44
	v_fmac_f32_e32 v92, v97, v45
	v_lshlrev_b32_e32 v96, 16, v39
	v_and_b32_e32 v97, 0xffff0000, v39
	v_fmac_f32_e32 v94, v96, v46
	v_fmac_f32_e32 v194, v97, v47
	v_lshlrev_b32_e32 v96, 16, v40
	v_and_b32_e32 v97, 0xffff0000, v40
	v_fmac_f32_e32 v61, v96, v48
	v_fmac_f32_e32 v71, v97, v49
	v_lshlrev_b32_e32 v96, 16, v41
	v_and_b32_e32 v97, 0xffff0000, v41
	v_fmac_f32_e32 v73, v96, v50
	v_fmac_f32_e32 v88, v97, v51
	v_lshlrev_b32_e32 v96, 16, v42
	v_and_b32_e32 v97, 0xffff0000, v42
	v_fmac_f32_e32 v90, v96, v128
	v_fmac_f32_e32 v92, v97, v129
	v_lshlrev_b32_e32 v96, 16, v43
	v_and_b32_e32 v97, 0xffff0000, v43
	v_fmac_f32_e32 v94, v96, v130
	v_fmac_f32_e32 v194, v97, v131
	v_mul_f32_e32 v101, 0xbfb8aa3b, v1
	v_exp_f32_e32 v101, v101
	s_nop 0
	v_add_f32_e32 v102, 1.0, v101
	v_div_scale_f32 v96, s[34:35], v102, v102, v1
	v_rcp_f32_e32 v97, v96
	v_div_scale_f32 v98, vcc, v1, v102, v1
	v_fma_f32 v99, -v96, v97, 1.0
	v_fmac_f32_e32 v97, v99, v97
	v_mul_f32_e32 v99, v98, v97
	v_fma_f32 v100, -v96, v99, v98
	v_fmac_f32_e32 v99, v100, v97
	v_fma_f32 v98, -v96, v99, v98
	v_div_fmas_f32 v98, v98, v97, v99
	v_div_fixup_f32 v103, v98, v102, v1
	v_mov_b32_e32 v1, v103
	v_mul_f32_e32 v101, 0xbfb8aa3b, v2
	v_exp_f32_e32 v101, v101
	s_nop 0
	v_add_f32_e32 v102, 1.0, v101
	v_div_scale_f32 v96, s[34:35], v102, v102, v2
	v_rcp_f32_e32 v97, v96
	v_div_scale_f32 v98, vcc, v2, v102, v2
	v_fma_f32 v99, -v96, v97, 1.0
	v_fmac_f32_e32 v97, v99, v97
	v_mul_f32_e32 v99, v98, v97
	v_fma_f32 v100, -v96, v99, v98
	v_fmac_f32_e32 v99, v100, v97
	v_fma_f32 v98, -v96, v99, v98
	v_div_fmas_f32 v98, v98, v97, v99
	v_div_fixup_f32 v103, v98, v102, v2
	v_mov_b32_e32 v2, v103
	v_mul_f32_e32 v101, 0xbfb8aa3b, v3
	v_exp_f32_e32 v101, v101
	s_nop 0
	v_add_f32_e32 v102, 1.0, v101
	v_div_scale_f32 v96, s[34:35], v102, v102, v3
	v_rcp_f32_e32 v97, v96
	v_div_scale_f32 v98, vcc, v3, v102, v3
	v_fma_f32 v99, -v96, v97, 1.0
	v_fmac_f32_e32 v97, v99, v97
	v_mul_f32_e32 v99, v98, v97
	v_fma_f32 v100, -v96, v99, v98
	v_fmac_f32_e32 v99, v100, v97
	v_fma_f32 v98, -v96, v99, v98
	v_div_fmas_f32 v98, v98, v97, v99
	v_div_fixup_f32 v103, v98, v102, v3
	v_mov_b32_e32 v3, v103
	v_mul_f32_e32 v101, 0xbfb8aa3b, v4
	v_exp_f32_e32 v101, v101
	s_nop 0
	v_add_f32_e32 v102, 1.0, v101
	v_div_scale_f32 v96, s[34:35], v102, v102, v4
	v_rcp_f32_e32 v97, v96
	v_div_scale_f32 v98, vcc, v4, v102, v4
	v_fma_f32 v99, -v96, v97, 1.0
	v_fmac_f32_e32 v97, v99, v97
	v_mul_f32_e32 v99, v98, v97
	v_fma_f32 v100, -v96, v99, v98
	v_fmac_f32_e32 v99, v100, v97
	v_fma_f32 v98, -v96, v99, v98
	v_div_fmas_f32 v98, v98, v97, v99
	v_div_fixup_f32 v103, v98, v102, v4
	v_mov_b32_e32 v4, v103
	v_mul_f32_e32 v101, 0xbfb8aa3b, v5
	v_exp_f32_e32 v101, v101
	s_nop 0
	v_add_f32_e32 v102, 1.0, v101
	v_div_scale_f32 v96, s[34:35], v102, v102, v5
	v_rcp_f32_e32 v97, v96
	v_div_scale_f32 v98, vcc, v5, v102, v5
	v_fma_f32 v99, -v96, v97, 1.0
	v_fmac_f32_e32 v97, v99, v97
	v_mul_f32_e32 v99, v98, v97
	v_fma_f32 v100, -v96, v99, v98
	v_fmac_f32_e32 v99, v100, v97
; DI float siluf(float x) { return x / (1.f + __expf(-x)); }
; DI void dn_prep(const Params& p, int item, char* smem) {
;     ...
;     for (int e = 0; e < 8; ++e) { y[e] = siluf(y[e]); ss += y[e] * y[e]; }
	v_fma_f32 v98, -v96, v99, v98
	v_div_fmas_f32 v98, v98, v97, v99
	v_div_fixup_f32 v103, v98, v102, v5
	v_mov_b32_e32 v5, v103
	v_mul_f32_e32 v101, 0xbfb8aa3b, v6
	v_exp_f32_e32 v101, v101
	s_nop 0
	v_add_f32_e32 v102, 1.0, v101
	v_div_scale_f32 v96, s[34:35], v102, v102, v6
	v_rcp_f32_e32 v97, v96
	v_div_scale_f32 v98, vcc, v6, v102, v6
	v_fma_f32 v99, -v96, v97, 1.0
	v_fmac_f32_e32 v97, v99, v97
	v_mul_f32_e32 v99, v98, v97
	v_fma_f32 v100, -v96, v99, v98
	v_fmac_f32_e32 v99, v100, v97
	v_fma_f32 v98, -v96, v99, v98
	v_div_fmas_f32 v98, v98, v97, v99
	v_div_fixup_f32 v103, v98, v102, v6
	v_mov_b32_e32 v6, v103
	v_mul_f32_e32 v101, 0xbfb8aa3b, v7
	v_exp_f32_e32 v101, v101
	s_nop 0
	v_add_f32_e32 v102, 1.0, v101
	v_div_scale_f32 v96, s[34:35], v102, v102, v7
	v_rcp_f32_e32 v97, v96
	v_div_scale_f32 v98, vcc, v7, v102, v7
	v_fma_f32 v99, -v96, v97, 1.0
	v_fmac_f32_e32 v97, v99, v97
	v_mul_f32_e32 v99, v98, v97
	v_fma_f32 v100, -v96, v99, v98
	v_fmac_f32_e32 v99, v100, v97
	v_fma_f32 v98, -v96, v99, v98
	v_div_fmas_f32 v98, v98, v97, v99
	v_div_fixup_f32 v103, v98, v102, v7
	v_mov_b32_e32 v7, v103
	v_mul_f32_e32 v101, 0xbfb8aa3b, v8
	v_exp_f32_e32 v101, v101
	s_nop 0
	v_add_f32_e32 v102, 1.0, v101
	v_div_scale_f32 v96, s[34:35], v102, v102, v8
	v_rcp_f32_e32 v97, v96
	v_div_scale_f32 v98, vcc, v8, v102, v8
	v_fma_f32 v99, -v96, v97, 1.0
	v_fmac_f32_e32 v97, v99, v97
	v_mul_f32_e32 v99, v98, v97
	v_fma_f32 v100, -v96, v99, v98
	v_fmac_f32_e32 v99, v100, v97
	v_fma_f32 v98, -v96, v99, v98
	v_div_fmas_f32 v98, v98, v97, v99
	v_div_fixup_f32 v103, v98, v102, v8
	v_mov_b32_e32 v8, v103
	v_mul_f32_e32 v101, 0xbfb8aa3b, v9
	v_exp_f32_e32 v101, v101
	s_nop 0
	v_add_f32_e32 v102, 1.0, v101
	v_div_scale_f32 v96, s[34:35], v102, v102, v9
	v_rcp_f32_e32 v97, v96
	v_div_scale_f32 v98, vcc, v9, v102, v9
	v_fma_f32 v99, -v96, v97, 1.0
	v_fmac_f32_e32 v97, v99, v97
	v_mul_f32_e32 v99, v98, v97
	v_fma_f32 v100, -v96, v99, v98
	v_fmac_f32_e32 v99, v100, v97
	v_fma_f32 v98, -v96, v99, v98
	v_div_fmas_f32 v98, v98, v97, v99
	v_div_fixup_f32 v103, v98, v102, v9
	v_mov_b32_e32 v9, v103
	v_mul_f32_e32 v101, 0xbfb8aa3b, v240
	v_exp_f32_e32 v101, v101
	s_nop 0
	v_add_f32_e32 v102, 1.0, v101
	v_div_scale_f32 v96, s[34:35], v102, v102, v240
	v_rcp_f32_e32 v97, v96
	v_div_scale_f32 v98, vcc, v240, v102, v240
	v_fma_f32 v99, -v96, v97, 1.0
	v_fmac_f32_e32 v97, v99, v97
	v_mul_f32_e32 v99, v98, v97
	v_fma_f32 v100, -v96, v99, v98
	v_fmac_f32_e32 v99, v100, v97
	v_fma_f32 v98, -v96, v99, v98
	v_div_fmas_f32 v98, v98, v97, v99
	v_div_fixup_f32 v103, v98, v102, v240
	v_mov_b32_e32 v240, v103
	v_mul_f32_e32 v101, 0xbfb8aa3b, v241
	v_exp_f32_e32 v101, v101
	s_nop 0
	v_add_f32_e32 v102, 1.0, v101
	v_div_scale_f32 v96, s[34:35], v102, v102, v241
	v_rcp_f32_e32 v97, v96
	v_div_scale_f32 v98, vcc, v241, v102, v241
	v_fma_f32 v99, -v96, v97, 1.0
	v_fmac_f32_e32 v97, v99, v97
	v_mul_f32_e32 v99, v98, v97
	v_fma_f32 v100, -v96, v99, v98
	v_fmac_f32_e32 v99, v100, v97
	v_fma_f32 v98, -v96, v99, v98
	v_div_fmas_f32 v98, v98, v97, v99
	v_div_fixup_f32 v103, v98, v102, v241
	v_mov_b32_e32 v241, v103
	v_mul_f32_e32 v101, 0xbfb8aa3b, v242
	v_exp_f32_e32 v101, v101
	s_nop 0
	v_add_f32_e32 v102, 1.0, v101
	v_div_scale_f32 v96, s[34:35], v102, v102, v242
	v_rcp_f32_e32 v97, v96
	v_div_scale_f32 v98, vcc, v242, v102, v242
	v_fma_f32 v99, -v96, v97, 1.0
	v_fmac_f32_e32 v97, v99, v97
	v_mul_f32_e32 v99, v98, v97
	v_fma_f32 v100, -v96, v99, v98
	v_fmac_f32_e32 v99, v100, v97
	v_fma_f32 v98, -v96, v99, v98
	v_div_fmas_f32 v98, v98, v97, v99
	v_div_fixup_f32 v103, v98, v102, v242
	v_mov_b32_e32 v242, v103
	v_mul_f32_e32 v101, 0xbfb8aa3b, v243
	v_exp_f32_e32 v101, v101
	s_nop 0
	v_add_f32_e32 v102, 1.0, v101
	v_div_scale_f32 v96, s[34:35], v102, v102, v243
	v_rcp_f32_e32 v97, v96
	v_div_scale_f32 v98, vcc, v243, v102, v243
	v_fma_f32 v99, -v96, v97, 1.0
	v_fmac_f32_e32 v97, v99, v97
	v_mul_f32_e32 v99, v98, v97
	v_fma_f32 v100, -v96, v99, v98
	v_fmac_f32_e32 v99, v100, v97
	v_fma_f32 v98, -v96, v99, v98
	v_div_fmas_f32 v98, v98, v97, v99
	v_div_fixup_f32 v103, v98, v102, v243
	v_mov_b32_e32 v243, v103
	v_mul_f32_e32 v101, 0xbfb8aa3b, v244
	v_exp_f32_e32 v101, v101
	s_nop 0
	v_add_f32_e32 v102, 1.0, v101
	v_div_scale_f32 v96, s[34:35], v102, v102, v244
	v_rcp_f32_e32 v97, v96
	v_div_scale_f32 v98, vcc, v244, v102, v244
	v_fma_f32 v99, -v96, v97, 1.0
	v_fmac_f32_e32 v97, v99, v97
	v_mul_f32_e32 v99, v98, v97
	v_fma_f32 v100, -v96, v99, v98
	v_fmac_f32_e32 v99, v100, v97
	v_fma_f32 v98, -v96, v99, v98
	v_div_fmas_f32 v98, v98, v97, v99
	v_div_fixup_f32 v103, v98, v102, v244
	v_mov_b32_e32 v244, v103
	v_mul_f32_e32 v101, 0xbfb8aa3b, v245
	v_exp_f32_e32 v101, v101
	s_nop 0
	v_add_f32_e32 v102, 1.0, v101
	v_div_scale_f32 v96, s[34:35], v102, v102, v245
	v_rcp_f32_e32 v97, v96
	v_div_scale_f32 v98, vcc, v245, v102, v245
	v_fma_f32 v99, -v96, v97, 1.0
	v_fmac_f32_e32 v97, v99, v97
	v_mul_f32_e32 v99, v98, v97
	v_fma_f32 v100, -v96, v99, v98
	v_fmac_f32_e32 v99, v100, v97
	v_fma_f32 v98, -v96, v99, v98
	v_div_fmas_f32 v98, v98, v97, v99
	v_div_fixup_f32 v103, v98, v102, v245
	v_mov_b32_e32 v245, v103
	v_mul_f32_e32 v101, 0xbfb8aa3b, v246
	v_exp_f32_e32 v101, v101
	s_nop 0
	v_add_f32_e32 v102, 1.0, v101
	v_div_scale_f32 v96, s[34:35], v102, v102, v246
	v_rcp_f32_e32 v97, v96
	v_div_scale_f32 v98, vcc, v246, v102, v246
	v_fma_f32 v99, -v96, v97, 1.0
	v_fmac_f32_e32 v97, v99, v97
	v_mul_f32_e32 v99, v98, v97
	v_fma_f32 v100, -v96, v99, v98
	v_fmac_f32_e32 v99, v100, v97
	v_fma_f32 v98, -v96, v99, v98
	v_div_fmas_f32 v98, v98, v97, v99
	v_div_fixup_f32 v103, v98, v102, v246
	v_mov_b32_e32 v246, v103
; DI float siluf(float x) { return x / (1.f + __expf(-x)); }
; DI void dn_prep(const Params& p, int item, char* smem) {
;     ...
;     for (int e = 0; e < 8; ++e) { y[e] = siluf(y[e]); ss += y[e] * y[e]; }
	v_mul_f32_e32 v101, 0xbfb8aa3b, v247
	v_exp_f32_e32 v101, v101
	s_nop 0
	v_add_f32_e32 v102, 1.0, v101
	v_div_scale_f32 v96, s[34:35], v102, v102, v247
	v_rcp_f32_e32 v97, v96
	v_div_scale_f32 v98, vcc, v247, v102, v247
	v_fma_f32 v99, -v96, v97, 1.0
	v_fmac_f32_e32 v97, v99, v97
	v_mul_f32_e32 v99, v98, v97
	v_fma_f32 v100, -v96, v99, v98
	v_fmac_f32_e32 v99, v100, v97
	v_fma_f32 v98, -v96, v99, v98
	v_div_fmas_f32 v98, v98, v97, v99
	v_div_fixup_f32 v103, v98, v102, v247
	v_mov_b32_e32 v247, v103
	v_mul_f32_e32 v101, 0xbfb8aa3b, v248
	v_exp_f32_e32 v101, v101
	s_nop 0
	v_add_f32_e32 v102, 1.0, v101
	v_div_scale_f32 v96, s[34:35], v102, v102, v248
	v_rcp_f32_e32 v97, v96
	v_div_scale_f32 v98, vcc, v248, v102, v248
	v_fma_f32 v99, -v96, v97, 1.0
	v_fmac_f32_e32 v97, v99, v97
	v_mul_f32_e32 v99, v98, v97
	v_fma_f32 v100, -v96, v99, v98
	v_fmac_f32_e32 v99, v100, v97
	v_fma_f32 v98, -v96, v99, v98
	v_div_fmas_f32 v98, v98, v97, v99
	v_div_fixup_f32 v103, v98, v102, v248
	v_mov_b32_e32 v248, v103
	v_mul_f32_e32 v101, 0xbfb8aa3b, v249
	v_exp_f32_e32 v101, v101
	s_nop 0
	v_add_f32_e32 v102, 1.0, v101
	v_div_scale_f32 v96, s[34:35], v102, v102, v249
	v_rcp_f32_e32 v97, v96
	v_div_scale_f32 v98, vcc, v249, v102, v249
	v_fma_f32 v99, -v96, v97, 1.0
	v_fmac_f32_e32 v97, v99, v97
	v_mul_f32_e32 v99, v98, v97
	v_fma_f32 v100, -v96, v99, v98
	v_fmac_f32_e32 v99, v100, v97
	v_fma_f32 v98, -v96, v99, v98
	v_div_fmas_f32 v98, v98, v97, v99
	v_div_fixup_f32 v103, v98, v102, v249
	v_mov_b32_e32 v249, v103
	v_mul_f32_e32 v101, 0xbfb8aa3b, v250
	v_exp_f32_e32 v101, v101
	s_nop 0
	v_add_f32_e32 v102, 1.0, v101
	v_div_scale_f32 v96, s[34:35], v102, v102, v250
	v_rcp_f32_e32 v97, v96
	v_div_scale_f32 v98, vcc, v250, v102, v250
	v_fma_f32 v99, -v96, v97, 1.0
	v_fmac_f32_e32 v97, v99, v97
	v_mul_f32_e32 v99, v98, v97
	v_fma_f32 v100, -v96, v99, v98
	v_fmac_f32_e32 v99, v100, v97
	v_fma_f32 v98, -v96, v99, v98
	v_div_fmas_f32 v98, v98, v97, v99
	v_div_fixup_f32 v103, v98, v102, v250
	v_mov_b32_e32 v250, v103
	v_mul_f32_e32 v101, 0xbfb8aa3b, v251
	v_exp_f32_e32 v101, v101
	s_nop 0
	v_add_f32_e32 v102, 1.0, v101
	v_div_scale_f32 v96, s[34:35], v102, v102, v251
	v_rcp_f32_e32 v97, v96
	v_div_scale_f32 v98, vcc, v251, v102, v251
	v_fma_f32 v99, -v96, v97, 1.0
	v_fmac_f32_e32 v97, v99, v97
	v_mul_f32_e32 v99, v98, v97
	v_fma_f32 v100, -v96, v99, v98
	v_fmac_f32_e32 v99, v100, v97
	v_fma_f32 v98, -v96, v99, v98
	v_div_fmas_f32 v98, v98, v97, v99
	v_div_fixup_f32 v103, v98, v102, v251
	v_mov_b32_e32 v251, v103
	v_mul_f32_e32 v101, 0xbfb8aa3b, v252
	v_exp_f32_e32 v101, v101
	s_nop 0
	v_add_f32_e32 v102, 1.0, v101
	v_div_scale_f32 v96, s[34:35], v102, v102, v252
	v_rcp_f32_e32 v97, v96
	v_div_scale_f32 v98, vcc, v252, v102, v252
	v_fma_f32 v99, -v96, v97, 1.0
	v_fmac_f32_e32 v97, v99, v97
	v_mul_f32_e32 v99, v98, v97
	v_fma_f32 v100, -v96, v99, v98
	v_fmac_f32_e32 v99, v100, v97
	v_fma_f32 v98, -v96, v99, v98
	v_div_fmas_f32 v98, v98, v97, v99
	v_div_fixup_f32 v103, v98, v102, v252
	v_mov_b32_e32 v252, v103
	v_mul_f32_e32 v101, 0xbfb8aa3b, v253
	v_exp_f32_e32 v101, v101
	s_nop 0
	v_add_f32_e32 v102, 1.0, v101
	v_div_scale_f32 v96, s[34:35], v102, v102, v253
	v_rcp_f32_e32 v97, v96
	v_div_scale_f32 v98, vcc, v253, v102, v253
	v_fma_f32 v99, -v96, v97, 1.0
	v_fmac_f32_e32 v97, v99, v97
	v_mul_f32_e32 v99, v98, v97
	v_fma_f32 v100, -v96, v99, v98
	v_fmac_f32_e32 v99, v100, v97
	v_fma_f32 v98, -v96, v99, v98
	v_div_fmas_f32 v98, v98, v97, v99
	v_div_fixup_f32 v103, v98, v102, v253
	v_mov_b32_e32 v253, v103
	v_mul_f32_e32 v101, 0xbfb8aa3b, v254
	v_exp_f32_e32 v101, v101
	s_nop 0
	v_add_f32_e32 v102, 1.0, v101
	v_div_scale_f32 v96, s[34:35], v102, v102, v254
	v_rcp_f32_e32 v97, v96
	v_div_scale_f32 v98, vcc, v254, v102, v254
	v_fma_f32 v99, -v96, v97, 1.0
	v_fmac_f32_e32 v97, v99, v97
	v_mul_f32_e32 v99, v98, v97
	v_fma_f32 v100, -v96, v99, v98
	v_fmac_f32_e32 v99, v100, v97
	v_fma_f32 v98, -v96, v99, v98
	v_div_fmas_f32 v98, v98, v97, v99
	v_div_fixup_f32 v103, v98, v102, v254
	v_mov_b32_e32 v254, v103
	v_mul_f32_e32 v101, 0xbfb8aa3b, v61
	v_exp_f32_e32 v101, v101
	s_nop 0
	v_add_f32_e32 v102, 1.0, v101
	v_div_scale_f32 v96, s[34:35], v102, v102, v61
	v_rcp_f32_e32 v97, v96
	v_div_scale_f32 v98, vcc, v61, v102, v61
	v_fma_f32 v99, -v96, v97, 1.0
	v_fmac_f32_e32 v97, v99, v97
	v_mul_f32_e32 v99, v98, v97
	v_fma_f32 v100, -v96, v99, v98
	v_fmac_f32_e32 v99, v100, v97
	v_fma_f32 v98, -v96, v99, v98
	v_div_fmas_f32 v98, v98, v97, v99
	v_div_fixup_f32 v103, v98, v102, v61
	v_mov_b32_e32 v61, v103
	v_mul_f32_e32 v101, 0xbfb8aa3b, v71
	v_exp_f32_e32 v101, v101
	s_nop 0
	v_add_f32_e32 v102, 1.0, v101
	v_div_scale_f32 v96, s[34:35], v102, v102, v71
	v_rcp_f32_e32 v97, v96
	v_div_scale_f32 v98, vcc, v71, v102, v71
	v_fma_f32 v99, -v96, v97, 1.0
	v_fmac_f32_e32 v97, v99, v97
	v_mul_f32_e32 v99, v98, v97
	v_fma_f32 v100, -v96, v99, v98
	v_fmac_f32_e32 v99, v100, v97
	v_fma_f32 v98, -v96, v99, v98
	v_div_fmas_f32 v98, v98, v97, v99
	v_div_fixup_f32 v103, v98, v102, v71
	v_mov_b32_e32 v71, v103
	v_mul_f32_e32 v101, 0xbfb8aa3b, v73
	v_exp_f32_e32 v101, v101
	s_nop 0
	v_add_f32_e32 v102, 1.0, v101
	v_div_scale_f32 v96, s[34:35], v102, v102, v73
	v_rcp_f32_e32 v97, v96
	v_div_scale_f32 v98, vcc, v73, v102, v73
	v_fma_f32 v99, -v96, v97, 1.0
	v_fmac_f32_e32 v97, v99, v97
	v_mul_f32_e32 v99, v98, v97
	v_fma_f32 v100, -v96, v99, v98
	v_fmac_f32_e32 v99, v100, v97
	v_fma_f32 v98, -v96, v99, v98
	v_div_fmas_f32 v98, v98, v97, v99
	v_div_fixup_f32 v103, v98, v102, v73
	v_mov_b32_e32 v73, v103
	v_mul_f32_e32 v101, 0xbfb8aa3b, v88
	v_exp_f32_e32 v101, v101
	s_nop 0
	v_add_f32_e32 v102, 1.0, v101
; DI float siluf(float x) { return x / (1.f + __expf(-x)); }
; DI void dn_prep(const Params& p, int item, char* smem) {
;     ...
;     float ss = 0.f;
; #pragma unroll
;     for (int e = 0; e < 8; ++e) { y[e] = siluf(y[e]); ss += y[e] * y[e]; }
;     ss += __shfl_xor(ss, 1); ss += __shfl_xor(ss, 2); ss += __shfl_xor(ss, 4); ss += __shfl_xor(ss, 8);
	v_div_scale_f32 v96, s[34:35], v102, v102, v88
	v_rcp_f32_e32 v97, v96
	v_div_scale_f32 v98, vcc, v88, v102, v88
	v_fma_f32 v99, -v96, v97, 1.0
	v_fmac_f32_e32 v97, v99, v97
	v_mul_f32_e32 v99, v98, v97
	v_fma_f32 v100, -v96, v99, v98
	v_fmac_f32_e32 v99, v100, v97
	v_fma_f32 v98, -v96, v99, v98
	v_div_fmas_f32 v98, v98, v97, v99
	v_div_fixup_f32 v103, v98, v102, v88
	v_mov_b32_e32 v88, v103
	v_mul_f32_e32 v101, 0xbfb8aa3b, v90
	v_exp_f32_e32 v101, v101
	s_nop 0
	v_add_f32_e32 v102, 1.0, v101
	v_div_scale_f32 v96, s[34:35], v102, v102, v90
	v_rcp_f32_e32 v97, v96
	v_div_scale_f32 v98, vcc, v90, v102, v90
	v_fma_f32 v99, -v96, v97, 1.0
	v_fmac_f32_e32 v97, v99, v97
	v_mul_f32_e32 v99, v98, v97
	v_fma_f32 v100, -v96, v99, v98
	v_fmac_f32_e32 v99, v100, v97
	v_fma_f32 v98, -v96, v99, v98
	v_div_fmas_f32 v98, v98, v97, v99
	v_div_fixup_f32 v103, v98, v102, v90
	v_mov_b32_e32 v90, v103
	v_mul_f32_e32 v101, 0xbfb8aa3b, v92
	v_exp_f32_e32 v101, v101
	s_nop 0
	v_add_f32_e32 v102, 1.0, v101
	v_div_scale_f32 v96, s[34:35], v102, v102, v92
	v_rcp_f32_e32 v97, v96
	v_div_scale_f32 v98, vcc, v92, v102, v92
	v_fma_f32 v99, -v96, v97, 1.0
	v_fmac_f32_e32 v97, v99, v97
	v_mul_f32_e32 v99, v98, v97
	v_fma_f32 v100, -v96, v99, v98
	v_fmac_f32_e32 v99, v100, v97
	v_fma_f32 v98, -v96, v99, v98
	v_div_fmas_f32 v98, v98, v97, v99
	v_div_fixup_f32 v103, v98, v102, v92
	v_mov_b32_e32 v92, v103
	v_mul_f32_e32 v101, 0xbfb8aa3b, v94
	v_exp_f32_e32 v101, v101
	s_nop 0
	v_add_f32_e32 v102, 1.0, v101
	v_div_scale_f32 v96, s[34:35], v102, v102, v94
	v_rcp_f32_e32 v97, v96
	v_div_scale_f32 v98, vcc, v94, v102, v94
	v_fma_f32 v99, -v96, v97, 1.0
	v_fmac_f32_e32 v97, v99, v97
	v_mul_f32_e32 v99, v98, v97
	v_fma_f32 v100, -v96, v99, v98
	v_fmac_f32_e32 v99, v100, v97
	v_fma_f32 v98, -v96, v99, v98
	v_div_fmas_f32 v98, v98, v97, v99
	v_div_fixup_f32 v103, v98, v102, v94
	v_mov_b32_e32 v94, v103
	v_mul_f32_e32 v101, 0xbfb8aa3b, v194
	v_exp_f32_e32 v101, v101
	s_nop 0
	v_add_f32_e32 v102, 1.0, v101
	v_div_scale_f32 v96, s[34:35], v102, v102, v194
	v_rcp_f32_e32 v97, v96
	v_div_scale_f32 v98, vcc, v194, v102, v194
	v_fma_f32 v99, -v96, v97, 1.0
	v_fmac_f32_e32 v97, v99, v97
	v_mul_f32_e32 v99, v98, v97
	v_fma_f32 v100, -v96, v99, v98
	v_fmac_f32_e32 v99, v100, v97
	v_fma_f32 v98, -v96, v99, v98
	v_div_fmas_f32 v98, v98, v97, v99
	v_div_fixup_f32 v103, v98, v102, v194
	v_mov_b32_e32 v194, v103
	v_mul_f32_e32 v104, v1, v1
	v_fmac_f32_e32 v104, v2, v2
	v_fmac_f32_e32 v104, v3, v3
	v_fmac_f32_e32 v104, v4, v4
	v_fmac_f32_e32 v104, v5, v5
	v_fmac_f32_e32 v104, v6, v6
	v_fmac_f32_e32 v104, v7, v7
	v_fmac_f32_e32 v104, v8, v8
	v_mul_f32_e32 v105, v9, v9
	v_fmac_f32_e32 v105, v240, v240
	v_fmac_f32_e32 v105, v241, v241
	v_fmac_f32_e32 v105, v242, v242
	v_fmac_f32_e32 v105, v243, v243
	v_fmac_f32_e32 v105, v244, v244
	v_fmac_f32_e32 v105, v245, v245
	v_fmac_f32_e32 v105, v246, v246
	v_mul_f32_e32 v106, v247, v247
	v_fmac_f32_e32 v106, v248, v248
	v_fmac_f32_e32 v106, v249, v249
	v_fmac_f32_e32 v106, v250, v250
	v_fmac_f32_e32 v106, v251, v251
	v_fmac_f32_e32 v106, v252, v252
	v_fmac_f32_e32 v106, v253, v253
	v_fmac_f32_e32 v106, v254, v254
	v_mul_f32_e32 v107, v61, v61
	v_fmac_f32_e32 v107, v71, v71
	v_fmac_f32_e32 v107, v73, v73
	v_fmac_f32_e32 v107, v88, v88
	v_fmac_f32_e32 v107, v90, v90
	v_fmac_f32_e32 v107, v92, v92
	v_fmac_f32_e32 v107, v94, v94
	v_fmac_f32_e32 v107, v194, v194
	v_and_b32_e32 v112, 63, v142
	v_xor_b32_e32 v113, 1, v112
	v_lshlrev_b32_e32 v113, 2, v113
	v_xor_b32_e32 v114, 2, v112
	v_lshlrev_b32_e32 v114, 2, v114
	v_xor_b32_e32 v115, 4, v112
	v_lshlrev_b32_e32 v115, 2, v115
	v_xor_b32_e32 v116, 8, v112
	v_lshlrev_b32_e32 v116, 2, v116
	ds_bpermute_b32 v108, v113, v104
	ds_bpermute_b32 v109, v113, v105
	ds_bpermute_b32 v110, v113, v106
	ds_bpermute_b32 v111, v113, v107
	s_waitcnt lgkmcnt(0)
	v_add_f32_e32 v104, v104, v108
	v_add_f32_e32 v105, v105, v109
	v_add_f32_e32 v106, v106, v110
	v_add_f32_e32 v107, v107, v111
	ds_bpermute_b32 v108, v114, v104
	ds_bpermute_b32 v109, v114, v105
	ds_bpermute_b32 v110, v114, v106
	ds_bpermute_b32 v111, v114, v107
	s_waitcnt lgkmcnt(0)
	v_add_f32_e32 v104, v104, v108
	v_add_f32_e32 v105, v105, v109
	v_add_f32_e32 v106, v106, v110
	v_add_f32_e32 v107, v107, v111
	ds_bpermute_b32 v108, v115, v104
	ds_bpermute_b32 v109, v115, v105
	ds_bpermute_b32 v110, v115, v106
	ds_bpermute_b32 v111, v115, v107
	s_waitcnt lgkmcnt(0)
	v_add_f32_e32 v104, v104, v108
	v_add_f32_e32 v105, v105, v109
	v_add_f32_e32 v106, v106, v110
	v_add_f32_e32 v107, v107, v111
	ds_bpermute_b32 v108, v116, v104
	ds_bpermute_b32 v109, v116, v105
	ds_bpermute_b32 v110, v116, v106
	ds_bpermute_b32 v111, v116, v107
	s_waitcnt lgkmcnt(0)
; DI unsigned pack2(float a, float b) { return (unsigned)f2bf(a) | ((unsigned)f2bf(b) << 16); }
; DI void dn_prep(const Params& p, int item, char* smem) {
;     ...
;     ss += __shfl_xor(ss, 1); ss += __shfl_xor(ss, 2); ss += __shfl_xor(ss, 4); ss += __shfl_xor(ss, 8);
;     float sc = rsqrtf(ss + EPS) * (part == 0 ? 0.08838834764831845f : 1.f);
;     uint4 o; o.x = pack2(y[0] * sc, y[1] * sc); o.y = pack2(y[2] * sc, y[3] * sc); o.z = pack2(y[4] * sc, y[5] * sc); o.w = pack2(y[6] * sc, y[7] * sc);
;     *(uint4*)&((part == 0 ? qs : ksm)[tt * 136 + sub * 8]) = o;
	v_add_f32_e32 v104, v104, v108
	v_add_f32_e32 v105, v105, v109
	v_add_f32_e32 v106, v106, v110
	v_add_f32_e32 v107, v107, v111
	v_add_f32_e32 v104, 0x358637bd, v104
	v_cmp_gt_f32_e32 vcc, 0x800000, v104
	v_mul_f32_e32 v108, 0x4b800000, v104
	s_nop 0
	v_cndmask_b32_e32 v104, v104, v108, vcc
	v_rsq_f32_e32 v104, v104
	s_nop 0
	v_mul_f32_e32 v108, 0x45800000, v104
	v_cndmask_b32_e32 v104, v104, v108, vcc
	v_mul_f32_e32 v104, 0x3db504f3, v104
	v_add_f32_e32 v105, 0x358637bd, v105
	v_cmp_gt_f32_e32 vcc, 0x800000, v105
	v_mul_f32_e32 v109, 0x4b800000, v105
	s_nop 0
	v_cndmask_b32_e32 v105, v105, v109, vcc
	v_rsq_f32_e32 v105, v105
	s_nop 0
	v_mul_f32_e32 v109, 0x45800000, v105
	v_cndmask_b32_e32 v105, v105, v109, vcc
	v_mul_f32_e32 v105, 0x3db504f3, v105
	v_add_f32_e32 v106, 0x358637bd, v106
	v_cmp_gt_f32_e32 vcc, 0x800000, v106
	v_mul_f32_e32 v110, 0x4b800000, v106
	s_nop 0
	v_cndmask_b32_e32 v106, v106, v110, vcc
	v_rsq_f32_e32 v106, v106
	s_nop 0
	v_mul_f32_e32 v110, 0x45800000, v106
	v_cndmask_b32_e32 v106, v106, v110, vcc
	v_mul_f32_e32 v106, 0x3db504f3, v106
	v_add_f32_e32 v107, 0x358637bd, v107
	v_cmp_gt_f32_e32 vcc, 0x800000, v107
	v_mul_f32_e32 v111, 0x4b800000, v107
	s_nop 0
	v_cndmask_b32_e32 v107, v107, v111, vcc
	v_rsq_f32_e32 v107, v107
	s_nop 0
	v_mul_f32_e32 v111, 0x45800000, v107
	v_cndmask_b32_e32 v107, v107, v111, vcc
	v_mul_f32_e32 v107, 0x3db504f3, v107
	s_movk_i32 s34, 0x7fff
	s_mov_b32 s35, 0x7060302
	v_lshrrev_b32_e32 v118, 4, v142
	v_and_b32_e32 v119, 15, v142
	v_mul_u32_u24_e32 v117, 0x110, v118
	v_lshl_add_u32 v117, v119, 4, v117
	v_mul_f32_e32 v1, v1, v104
	v_bfe_u32 v108, v1, 16, 1
	v_add3_u32 v1, v1, v108, s34
	v_mul_f32_e32 v2, v2, v104
	v_bfe_u32 v108, v2, 16, 1
	v_add3_u32 v2, v2, v108, s34
	v_mul_f32_e32 v3, v3, v104
	v_bfe_u32 v108, v3, 16, 1
	v_add3_u32 v3, v3, v108, s34
	v_mul_f32_e32 v4, v4, v104
	v_bfe_u32 v108, v4, 16, 1
	v_add3_u32 v4, v4, v108, s34
	v_mul_f32_e32 v5, v5, v104
	v_bfe_u32 v108, v5, 16, 1
	v_add3_u32 v5, v5, v108, s34
	v_mul_f32_e32 v6, v6, v104
	v_bfe_u32 v108, v6, 16, 1
	v_add3_u32 v6, v6, v108, s34
	v_mul_f32_e32 v7, v7, v104
	v_bfe_u32 v108, v7, 16, 1
	v_add3_u32 v7, v7, v108, s34
	v_mul_f32_e32 v8, v8, v104
	v_bfe_u32 v108, v8, 16, 1
	v_add3_u32 v8, v8, v108, s34
	v_perm_b32 v120, v2, v1, s35
	v_perm_b32 v121, v4, v3, s35
	v_perm_b32 v122, v6, v5, s35
	v_perm_b32 v123, v8, v7, s35
	ds_write_b128 v117, v[120:123] offset:0
	s_nop 0
	v_mul_f32_e32 v9, v9, v105
	v_bfe_u32 v108, v9, 16, 1
	v_add3_u32 v9, v9, v108, s34
	v_mul_f32_e32 v240, v240, v105
	v_bfe_u32 v108, v240, 16, 1
	v_add3_u32 v240, v240, v108, s34
	v_mul_f32_e32 v241, v241, v105
	v_bfe_u32 v108, v241, 16, 1
	v_add3_u32 v241, v241, v108, s34
	v_mul_f32_e32 v242, v242, v105
	v_bfe_u32 v108, v242, 16, 1
	v_add3_u32 v242, v242, v108, s34
	v_mul_f32_e32 v243, v243, v105
	v_bfe_u32 v108, v243, 16, 1
	v_add3_u32 v243, v243, v108, s34
	v_mul_f32_e32 v244, v244, v105
	v_bfe_u32 v108, v244, 16, 1
	v_add3_u32 v244, v244, v108, s34
	v_mul_f32_e32 v245, v245, v105
	v_bfe_u32 v108, v245, 16, 1
	v_add3_u32 v245, v245, v108, s34
	v_mul_f32_e32 v246, v246, v105
	v_bfe_u32 v108, v246, 16, 1
	v_add3_u32 v246, v246, v108, s34
	v_perm_b32 v120, v240, v9, s35
	v_perm_b32 v121, v242, v241, s35
	v_perm_b32 v122, v244, v243, s35
	v_perm_b32 v123, v246, v245, s35
	ds_write_b128 v117, v[120:123] offset:4352
	s_nop 0
	v_mul_f32_e32 v247, v247, v106
	v_bfe_u32 v108, v247, 16, 1
	v_add3_u32 v247, v247, v108, s34
	v_mul_f32_e32 v248, v248, v106
	v_bfe_u32 v108, v248, 16, 1
	v_add3_u32 v248, v248, v108, s34
	v_mul_f32_e32 v249, v249, v106
	v_bfe_u32 v108, v249, 16, 1
	v_add3_u32 v249, v249, v108, s34
	v_mul_f32_e32 v250, v250, v106
	v_bfe_u32 v108, v250, 16, 1
	v_add3_u32 v250, v250, v108, s34
	v_mul_f32_e32 v251, v251, v106
	v_bfe_u32 v108, v251, 16, 1
	v_add3_u32 v251, v251, v108, s34
	v_mul_f32_e32 v252, v252, v106
	v_bfe_u32 v108, v252, 16, 1
	v_add3_u32 v252, v252, v108, s34
	v_mul_f32_e32 v253, v253, v106
	v_bfe_u32 v108, v253, 16, 1
	v_add3_u32 v253, v253, v108, s34
	v_mul_f32_e32 v254, v254, v106
	v_bfe_u32 v108, v254, 16, 1
	v_add3_u32 v254, v254, v108, s34
	v_perm_b32 v120, v248, v247, s35
	v_perm_b32 v121, v250, v249, s35
	v_perm_b32 v122, v252, v251, s35
	v_perm_b32 v123, v254, v253, s35
	ds_write_b128 v117, v[120:123] offset:8704
	s_nop 0
	v_mul_f32_e32 v61, v61, v107
	v_bfe_u32 v108, v61, 16, 1
	v_add3_u32 v61, v61, v108, s34
	v_mul_f32_e32 v71, v71, v107
	v_bfe_u32 v108, v71, 16, 1
	v_add3_u32 v71, v71, v108, s34
	v_mul_f32_e32 v73, v73, v107
	v_bfe_u32 v108, v73, 16, 1
	v_add3_u32 v73, v73, v108, s34
	v_mul_f32_e32 v88, v88, v107
	v_bfe_u32 v108, v88, 16, 1
	v_add3_u32 v88, v88, v108, s34
	v_mul_f32_e32 v90, v90, v107
	v_bfe_u32 v108, v90, 16, 1
	v_add3_u32 v90, v90, v108, s34
	v_mul_f32_e32 v92, v92, v107
	v_bfe_u32 v108, v92, 16, 1
	v_add3_u32 v92, v92, v108, s34
	v_mul_f32_e32 v94, v94, v107
	v_bfe_u32 v108, v94, 16, 1
	v_add3_u32 v94, v94, v108, s34
	v_mul_f32_e32 v194, v194, v107
	v_bfe_u32 v108, v194, 16, 1
	v_add3_u32 v194, v194, v108, s34
	v_perm_b32 v120, v71, v61, s35
	v_perm_b32 v121, v88, v73, s35
	v_perm_b32 v122, v92, v90, s35
	v_perm_b32 v123, v194, v94, s35
	ds_write_b128 v117, v[120:123] offset:13056
	s_nop 0
	v_lshrrev_b32_e32 v195, 4, v142
	v_and_b32_e32 v194, 15, v142
	v_mul_u32_u24_e32 v195, 0x2200, v195
	v_lshl_add_u32 v195, v194, 4, v195
	v_lshlrev_b32_e32 v94, 5, v194
	v_mov_b32_e32 v90, 0x10160
	v_mov_b32_e32 v92, 0x10058
	ds_read_b64 v[96:97], v90
	ds_read_b64 v[100:101], v92
	s_waitcnt lgkmcnt(0)
; DI float bflo(unsigned d) { return __uint_as_float(d << 16); }
; DI float bfhi(unsigned d) { return __uint_as_float(d & 0xffff0000u); }
; DI void dn_prep(const Params& p, int item, char* smem) {
;     ...
;   for (int ps = 0; ps < 8; ++ps) {
;     const int combo = ps * 16 + (tid >> 4);
;     const int tt = combo & 63, part = combo >> 6, sub = tid & 15;
;     const int col = part * 512 + h * 128 + sub * 8;
;     float y[8] = {0.f, 0.f, 0.f, 0.f, 0.f, 0.f, 0.f, 0.f};
; #pragma unroll
;     for (int j = 0; j < 4; ++j) {
;       const int t = t0 + tt - 3 + j;
;       if (t >= 0) {
;         uint4 xv = *(const uint4*)&p.proj[(rowbase + t) * NP + col];
;         float4 wa = *(const float4*)&p.conv_w[j * 1536 + col], wb = *(const float4*)&p.conv_w[j * 1536 + col + 4];
;         y[0] += bflo(xv.x) * wa.x; y[1] += bfhi(xv.x) * wa.y; y[2] += bflo(xv.y) * wa.z; y[3] += bfhi(xv.y) * wa.w;
;         y[4] += bflo(xv.z) * wb.x; y[5] += bfhi(xv.z) * wb.y; y[6] += bflo(xv.w) * wb.z; y[7] += bfhi(xv.w) * wb.w;
	v_readfirstlane_b32 s98, v96
	v_readfirstlane_b32 s99, v97
	v_readfirstlane_b32 s100, v100
	v_readfirstlane_b32 s101, v101
	s_lshl_b32 s34, s30, 8
	s_add_i32 s34, s34, s31
	s_add_i32 s34, s34, 0x400
	s_ashr_i32 s35, s34, 31
	s_add_u32 s98, s98, s34
	s_addc_u32 s99, s99, s35
	s_lshl_b32 s34, s30, 9
	s_add_i32 s34, s34, 0x800
	s_add_u32 s100, s100, s34
	s_addc_u32 s101, s101, 0
	s_nop 1
	global_load_dwordx4 v[96:99], v195, s[98:99]
	s_add_u32 s98, s98, 0x2200
	s_addc_u32 s99, s99, 0
	global_load_dwordx4 v[100:103], v195, s[98:99]
	s_add_u32 s98, s98, 0x2200
	s_addc_u32 s99, s99, 0
	global_load_dwordx4 v[104:107], v195, s[98:99]
	s_add_u32 s98, s98, 0x2200
	s_addc_u32 s99, s99, 0
	global_load_dwordx4 v[108:111], v195, s[98:99]
	s_add_u32 s98, s98, 0x1ba00
	s_addc_u32 s99, s99, 0
	global_load_dwordx4 v[112:115], v195, s[98:99]
	s_add_u32 s98, s98, 0x2200
	s_addc_u32 s99, s99, 0
	global_load_dwordx4 v[116:119], v195, s[98:99]
	s_add_u32 s98, s98, 0x2200
	s_addc_u32 s99, s99, 0
	global_load_dwordx4 v[120:123], v195, s[98:99]
	s_add_u32 s98, s98, 0x2200
	s_addc_u32 s99, s99, 0
	global_load_dwordx4 v[124:127], v195, s[98:99]
	s_add_u32 s98, s98, 0x1ba00
	s_addc_u32 s99, s99, 0
	global_load_dwordx4 v[12:15], v195, s[98:99]
	s_add_u32 s98, s98, 0x2200
	s_addc_u32 s99, s99, 0
	global_load_dwordx4 v[16:19], v195, s[98:99]
	s_add_u32 s98, s98, 0x2200
	s_addc_u32 s99, s99, 0
	global_load_dwordx4 v[20:23], v195, s[98:99]
	s_add_u32 s98, s98, 0x2200
	s_addc_u32 s99, s99, 0
	global_load_dwordx4 v[24:27], v195, s[98:99]
	s_add_u32 s98, s98, 0x1ba00
	s_addc_u32 s99, s99, 0
	global_load_dwordx4 v[28:31], v195, s[98:99]
	s_add_u32 s98, s98, 0x2200
	s_addc_u32 s99, s99, 0
	global_load_dwordx4 v[32:35], v195, s[98:99]
	s_add_u32 s98, s98, 0x2200
	s_addc_u32 s99, s99, 0
	global_load_dwordx4 v[36:39], v195, s[98:99]
	s_add_u32 s98, s98, 0x2200
	s_addc_u32 s99, s99, 0
	global_load_dwordx4 v[40:43], v195, s[98:99]
	global_load_dwordx4 v[152:155], v94, s[100:101]
	global_load_dwordx4 v[156:159], v94, s[100:101] offset:16
	s_add_u32 s100, s100, 0x1800
	s_addc_u32 s101, s101, 0
	global_load_dwordx4 v[160:163], v94, s[100:101]
	global_load_dwordx4 v[164:167], v94, s[100:101] offset:16
	s_add_u32 s100, s100, 0x1800
	s_addc_u32 s101, s101, 0
	global_load_dwordx4 v[168:171], v94, s[100:101]
	global_load_dwordx4 v[44:47], v94, s[100:101] offset:16
	s_add_u32 s100, s100, 0x1800
	s_addc_u32 s101, s101, 0
	global_load_dwordx4 v[48:51], v94, s[100:101]
	global_load_dwordx4 v[128:131], v94, s[100:101] offset:16
	s_waitcnt vmcnt(0)
	s_and_b32 s34, s2, 0x7f
	s_cmp_lg_u32 s34, 0
	s_cbranch_scc1 .Ls1_nomask1
	v_lshrrev_b32_e32 v90, 4, v142
	v_cmp_gt_u32_e32 vcc, 3, v90
	s_nop 1
	v_cndmask_b32_e64 v96, v96, 0, vcc
	v_cndmask_b32_e64 v97, v97, 0, vcc
	v_cndmask_b32_e64 v98, v98, 0, vcc
	v_cndmask_b32_e64 v99, v99, 0, vcc
	v_cmp_gt_u32_e32 vcc, 2, v90
	s_nop 1
	v_cndmask_b32_e64 v100, v100, 0, vcc
	v_cndmask_b32_e64 v101, v101, 0, vcc
	v_cndmask_b32_e64 v102, v102, 0, vcc
	v_cndmask_b32_e64 v103, v103, 0, vcc
	v_cmp_gt_u32_e32 vcc, 1, v90
	s_nop 1
	v_cndmask_b32_e64 v104, v104, 0, vcc
	v_cndmask_b32_e64 v105, v105, 0, vcc
	v_cndmask_b32_e64 v106, v106, 0, vcc
	v_cndmask_b32_e64 v107, v107, 0, vcc
.Ls1_nomask1:
	v_lshlrev_b32_e32 v90, 16, v96
	v_and_b32_e32 v92, 0xffff0000, v96
	v_mul_f32_e32 v1, v90, v152
	v_mul_f32_e32 v2, v92, v153
	v_lshlrev_b32_e32 v90, 16, v97
	v_and_b32_e32 v92, 0xffff0000, v97
	v_mul_f32_e32 v3, v90, v154
	v_mul_f32_e32 v4, v92, v155
	v_lshlrev_b32_e32 v90, 16, v98
	v_and_b32_e32 v92, 0xffff0000, v98
	v_mul_f32_e32 v5, v90, v156
	v_mul_f32_e32 v6, v92, v157
	v_lshlrev_b32_e32 v90, 16, v99
	v_and_b32_e32 v92, 0xffff0000, v99
	v_mul_f32_e32 v7, v90, v158
	v_mul_f32_e32 v8, v92, v159
	v_lshlrev_b32_e32 v90, 16, v100
	v_and_b32_e32 v92, 0xffff0000, v100
	v_fmac_f32_e32 v1, v90, v160
	v_fmac_f32_e32 v2, v92, v161
	v_lshlrev_b32_e32 v90, 16, v101
	v_and_b32_e32 v92, 0xffff0000, v101
	v_fmac_f32_e32 v3, v90, v162
	v_fmac_f32_e32 v4, v92, v163
	v_lshlrev_b32_e32 v90, 16, v102
	v_and_b32_e32 v92, 0xffff0000, v102
	v_fmac_f32_e32 v5, v90, v164
	v_fmac_f32_e32 v6, v92, v165
	v_lshlrev_b32_e32 v90, 16, v103
	v_and_b32_e32 v92, 0xffff0000, v103
	v_fmac_f32_e32 v7, v90, v166
	v_fmac_f32_e32 v8, v92, v167
	v_lshlrev_b32_e32 v90, 16, v104
	v_and_b32_e32 v92, 0xffff0000, v104
	v_fmac_f32_e32 v1, v90, v168
	v_fmac_f32_e32 v2, v92, v169
	v_lshlrev_b32_e32 v90, 16, v105
	v_and_b32_e32 v92, 0xffff0000, v105
	v_fmac_f32_e32 v3, v90, v170
	v_fmac_f32_e32 v4, v92, v171
	v_lshlrev_b32_e32 v90, 16, v106
	v_and_b32_e32 v92, 0xffff0000, v106
	v_fmac_f32_e32 v5, v90, v44
	v_fmac_f32_e32 v6, v92, v45
	v_lshlrev_b32_e32 v90, 16, v107
	v_and_b32_e32 v92, 0xffff0000, v107
	v_fmac_f32_e32 v7, v90, v46
	v_fmac_f32_e32 v8, v92, v47
	v_lshlrev_b32_e32 v90, 16, v108
	v_and_b32_e32 v92, 0xffff0000, v108
	v_fmac_f32_e32 v1, v90, v48
	v_fmac_f32_e32 v2, v92, v49
	v_lshlrev_b32_e32 v90, 16, v109
	v_and_b32_e32 v92, 0xffff0000, v109
	v_fmac_f32_e32 v3, v90, v50
	v_fmac_f32_e32 v4, v92, v51
	v_lshlrev_b32_e32 v90, 16, v110
	v_and_b32_e32 v92, 0xffff0000, v110
	v_fmac_f32_e32 v5, v90, v128
	v_fmac_f32_e32 v6, v92, v129
	v_lshlrev_b32_e32 v90, 16, v111
	v_and_b32_e32 v92, 0xffff0000, v111
	v_fmac_f32_e32 v7, v90, v130
	v_fmac_f32_e32 v8, v92, v131
	v_lshlrev_b32_e32 v90, 16, v112
	v_and_b32_e32 v92, 0xffff0000, v112
	v_mul_f32_e32 v9, v90, v152
	v_mul_f32_e32 v240, v92, v153
	v_lshlrev_b32_e32 v90, 16, v113
	v_and_b32_e32 v92, 0xffff0000, v113
	v_mul_f32_e32 v241, v90, v154
	v_mul_f32_e32 v242, v92, v155
	v_lshlrev_b32_e32 v90, 16, v114
	v_and_b32_e32 v92, 0xffff0000, v114
	v_mul_f32_e32 v243, v90, v156
; DI float bflo(unsigned d) { return __uint_as_float(d << 16); }
; DI float bfhi(unsigned d) { return __uint_as_float(d & 0xffff0000u); }
; DI void dn_prep(const Params& p, int item, char* smem) {
;     ...
;         y[0] += bflo(xv.x) * wa.x; y[1] += bfhi(xv.x) * wa.y; y[2] += bflo(xv.y) * wa.z; y[3] += bfhi(xv.y) * wa.w;
;         y[4] += bflo(xv.z) * wb.x; y[5] += bfhi(xv.z) * wb.y; y[6] += bflo(xv.w) * wb.z; y[7] += bfhi(xv.w) * wb.w;
	v_mul_f32_e32 v244, v92, v157
	v_lshlrev_b32_e32 v90, 16, v115
	v_and_b32_e32 v92, 0xffff0000, v115
	v_mul_f32_e32 v245, v90, v158
	v_mul_f32_e32 v246, v92, v159
	v_lshlrev_b32_e32 v90, 16, v116
	v_and_b32_e32 v92, 0xffff0000, v116
	v_fmac_f32_e32 v9, v90, v160
	v_fmac_f32_e32 v240, v92, v161
	v_lshlrev_b32_e32 v90, 16, v117
	v_and_b32_e32 v92, 0xffff0000, v117
	v_fmac_f32_e32 v241, v90, v162
	v_fmac_f32_e32 v242, v92, v163
	v_lshlrev_b32_e32 v90, 16, v118
	v_and_b32_e32 v92, 0xffff0000, v118
	v_fmac_f32_e32 v243, v90, v164
	v_fmac_f32_e32 v244, v92, v165
	v_lshlrev_b32_e32 v90, 16, v119
	v_and_b32_e32 v92, 0xffff0000, v119
	v_fmac_f32_e32 v245, v90, v166
	v_fmac_f32_e32 v246, v92, v167
	v_lshlrev_b32_e32 v90, 16, v120
	v_and_b32_e32 v92, 0xffff0000, v120
	v_fmac_f32_e32 v9, v90, v168
	v_fmac_f32_e32 v240, v92, v169
	v_lshlrev_b32_e32 v90, 16, v121
	v_and_b32_e32 v92, 0xffff0000, v121
	v_fmac_f32_e32 v241, v90, v170
	v_fmac_f32_e32 v242, v92, v171
	v_lshlrev_b32_e32 v90, 16, v122
	v_and_b32_e32 v92, 0xffff0000, v122
	v_fmac_f32_e32 v243, v90, v44
	v_fmac_f32_e32 v244, v92, v45
	v_lshlrev_b32_e32 v90, 16, v123
	v_and_b32_e32 v92, 0xffff0000, v123
	v_fmac_f32_e32 v245, v90, v46
	v_fmac_f32_e32 v246, v92, v47
	v_lshlrev_b32_e32 v90, 16, v124
	v_and_b32_e32 v92, 0xffff0000, v124
	v_fmac_f32_e32 v9, v90, v48
	v_fmac_f32_e32 v240, v92, v49
	v_lshlrev_b32_e32 v90, 16, v125
	v_and_b32_e32 v92, 0xffff0000, v125
	v_fmac_f32_e32 v241, v90, v50
	v_fmac_f32_e32 v242, v92, v51
	v_lshlrev_b32_e32 v90, 16, v126
	v_and_b32_e32 v92, 0xffff0000, v126
	v_fmac_f32_e32 v243, v90, v128
	v_fmac_f32_e32 v244, v92, v129
	v_lshlrev_b32_e32 v90, 16, v127
	v_and_b32_e32 v92, 0xffff0000, v127
	v_fmac_f32_e32 v245, v90, v130
	v_fmac_f32_e32 v246, v92, v131
	v_lshlrev_b32_e32 v90, 16, v12
	v_and_b32_e32 v92, 0xffff0000, v12
	v_mul_f32_e32 v247, v90, v152
	v_mul_f32_e32 v248, v92, v153
	v_lshlrev_b32_e32 v90, 16, v13
	v_and_b32_e32 v92, 0xffff0000, v13
	v_mul_f32_e32 v249, v90, v154
	v_mul_f32_e32 v250, v92, v155
	v_lshlrev_b32_e32 v90, 16, v14
	v_and_b32_e32 v92, 0xffff0000, v14
	v_mul_f32_e32 v251, v90, v156
	v_mul_f32_e32 v252, v92, v157
	v_lshlrev_b32_e32 v90, 16, v15
	v_and_b32_e32 v92, 0xffff0000, v15
	v_mul_f32_e32 v253, v90, v158
	v_mul_f32_e32 v254, v92, v159
	v_lshlrev_b32_e32 v90, 16, v16
	v_and_b32_e32 v92, 0xffff0000, v16
	v_fmac_f32_e32 v247, v90, v160
	v_fmac_f32_e32 v248, v92, v161
	v_lshlrev_b32_e32 v90, 16, v17
	v_and_b32_e32 v92, 0xffff0000, v17
	v_fmac_f32_e32 v249, v90, v162
	v_fmac_f32_e32 v250, v92, v163
	v_lshlrev_b32_e32 v90, 16, v18
	v_and_b32_e32 v92, 0xffff0000, v18
	v_fmac_f32_e32 v251, v90, v164
	v_fmac_f32_e32 v252, v92, v165
	v_lshlrev_b32_e32 v90, 16, v19
	v_and_b32_e32 v92, 0xffff0000, v19
	v_fmac_f32_e32 v253, v90, v166
	v_fmac_f32_e32 v254, v92, v167
	v_lshlrev_b32_e32 v90, 16, v20
	v_and_b32_e32 v92, 0xffff0000, v20
	v_fmac_f32_e32 v247, v90, v168
	v_fmac_f32_e32 v248, v92, v169
	v_lshlrev_b32_e32 v90, 16, v21
	v_and_b32_e32 v92, 0xffff0000, v21
	v_fmac_f32_e32 v249, v90, v170
	v_fmac_f32_e32 v250, v92, v171
	v_lshlrev_b32_e32 v90, 16, v22
	v_and_b32_e32 v92, 0xffff0000, v22
	v_fmac_f32_e32 v251, v90, v44
	v_fmac_f32_e32 v252, v92, v45
	v_lshlrev_b32_e32 v90, 16, v23
	v_and_b32_e32 v92, 0xffff0000, v23
	v_fmac_f32_e32 v253, v90, v46
	v_fmac_f32_e32 v254, v92, v47
	v_lshlrev_b32_e32 v90, 16, v24
	v_and_b32_e32 v92, 0xffff0000, v24
	v_fmac_f32_e32 v247, v90, v48
	v_fmac_f32_e32 v248, v92, v49
	v_lshlrev_b32_e32 v90, 16, v25
	v_and_b32_e32 v92, 0xffff0000, v25
	v_fmac_f32_e32 v249, v90, v50
	v_fmac_f32_e32 v250, v92, v51
	v_lshlrev_b32_e32 v90, 16, v26
	v_and_b32_e32 v92, 0xffff0000, v26
	v_fmac_f32_e32 v251, v90, v128
	v_fmac_f32_e32 v252, v92, v129
	v_lshlrev_b32_e32 v90, 16, v27
	v_and_b32_e32 v92, 0xffff0000, v27
	v_fmac_f32_e32 v253, v90, v130
	v_fmac_f32_e32 v254, v92, v131
	v_lshlrev_b32_e32 v96, 16, v28
	v_and_b32_e32 v97, 0xffff0000, v28
	v_mul_f32_e32 v61, v96, v152
	v_mul_f32_e32 v71, v97, v153
	v_lshlrev_b32_e32 v96, 16, v29
	v_and_b32_e32 v97, 0xffff0000, v29
	v_mul_f32_e32 v73, v96, v154
	v_mul_f32_e32 v88, v97, v155
	v_lshlrev_b32_e32 v96, 16, v30
	v_and_b32_e32 v97, 0xffff0000, v30
	v_mul_f32_e32 v90, v96, v156
	v_mul_f32_e32 v92, v97, v157
	v_lshlrev_b32_e32 v96, 16, v31
	v_and_b32_e32 v97, 0xffff0000, v31
	v_mul_f32_e32 v94, v96, v158
	v_mul_f32_e32 v194, v97, v159
	v_lshlrev_b32_e32 v96, 16, v32
	v_and_b32_e32 v97, 0xffff0000, v32
	v_fmac_f32_e32 v61, v96, v160
	v_fmac_f32_e32 v71, v97, v161
	v_lshlrev_b32_e32 v96, 16, v33
	v_and_b32_e32 v97, 0xffff0000, v33
	v_fmac_f32_e32 v73, v96, v162
	v_fmac_f32_e32 v88, v97, v163
	v_lshlrev_b32_e32 v96, 16, v34
	v_and_b32_e32 v97, 0xffff0000, v34
	v_fmac_f32_e32 v90, v96, v164
	v_fmac_f32_e32 v92, v97, v165
	v_lshlrev_b32_e32 v96, 16, v35
	v_and_b32_e32 v97, 0xffff0000, v35
	v_fmac_f32_e32 v94, v96, v166
	v_fmac_f32_e32 v194, v97, v167
	v_lshlrev_b32_e32 v96, 16, v36
	v_and_b32_e32 v97, 0xffff0000, v36
	v_fmac_f32_e32 v61, v96, v168
	v_fmac_f32_e32 v71, v97, v169
	v_lshlrev_b32_e32 v96, 16, v37
	v_and_b32_e32 v97, 0xffff0000, v37
	v_fmac_f32_e32 v73, v96, v170
	v_fmac_f32_e32 v88, v97, v171
	v_lshlrev_b32_e32 v96, 16, v38
	v_and_b32_e32 v97, 0xffff0000, v38
	v_fmac_f32_e32 v90, v96, v44
	v_fmac_f32_e32 v92, v97, v45
	v_lshlrev_b32_e32 v96, 16, v39
	v_and_b32_e32 v97, 0xffff0000, v39
	v_fmac_f32_e32 v94, v96, v46
	v_fmac_f32_e32 v194, v97, v47
	v_lshlrev_b32_e32 v96, 16, v40
	v_and_b32_e32 v97, 0xffff0000, v40
	v_fmac_f32_e32 v61, v96, v48
	v_fmac_f32_e32 v71, v97, v49
	v_lshlrev_b32_e32 v96, 16, v41
	v_and_b32_e32 v97, 0xffff0000, v41
	v_fmac_f32_e32 v73, v96, v50
; DI float bflo(unsigned d) { return __uint_as_float(d << 16); }
; DI float bfhi(unsigned d) { return __uint_as_float(d & 0xffff0000u); }
; DI float siluf(float x) { return x / (1.f + __expf(-x)); }
; DI void dn_prep(const Params& p, int item, char* smem) {
;     ...
;         y[0] += bflo(xv.x) * wa.x; y[1] += bfhi(xv.x) * wa.y; y[2] += bflo(xv.y) * wa.z; y[3] += bfhi(xv.y) * wa.w;
;         y[4] += bflo(xv.z) * wb.x; y[5] += bfhi(xv.z) * wb.y; y[6] += bflo(xv.w) * wb.z; y[7] += bfhi(xv.w) * wb.w;
;       }
;     }
;     float ss = 0.f;
; #pragma unroll
;     for (int e = 0; e < 8; ++e) { y[e] = siluf(y[e]); ss += y[e] * y[e]; }
	v_fmac_f32_e32 v88, v97, v51
	v_lshlrev_b32_e32 v96, 16, v42
	v_and_b32_e32 v97, 0xffff0000, v42
	v_fmac_f32_e32 v90, v96, v128
	v_fmac_f32_e32 v92, v97, v129
	v_lshlrev_b32_e32 v96, 16, v43
	v_and_b32_e32 v97, 0xffff0000, v43
	v_fmac_f32_e32 v94, v96, v130
	v_fmac_f32_e32 v194, v97, v131
	v_mul_f32_e32 v101, 0xbfb8aa3b, v1
	v_exp_f32_e32 v101, v101
	s_nop 0
	v_add_f32_e32 v102, 1.0, v101
	v_div_scale_f32 v96, s[34:35], v102, v102, v1
	v_rcp_f32_e32 v97, v96
	v_div_scale_f32 v98, vcc, v1, v102, v1
	v_fma_f32 v99, -v96, v97, 1.0
	v_fmac_f32_e32 v97, v99, v97
	v_mul_f32_e32 v99, v98, v97
	v_fma_f32 v100, -v96, v99, v98
	v_fmac_f32_e32 v99, v100, v97
	v_fma_f32 v98, -v96, v99, v98
	v_div_fmas_f32 v98, v98, v97, v99
	v_div_fixup_f32 v103, v98, v102, v1
	v_mov_b32_e32 v1, v103
	v_mul_f32_e32 v101, 0xbfb8aa3b, v2
	v_exp_f32_e32 v101, v101
	s_nop 0
	v_add_f32_e32 v102, 1.0, v101
	v_div_scale_f32 v96, s[34:35], v102, v102, v2
	v_rcp_f32_e32 v97, v96
	v_div_scale_f32 v98, vcc, v2, v102, v2
	v_fma_f32 v99, -v96, v97, 1.0
	v_fmac_f32_e32 v97, v99, v97
	v_mul_f32_e32 v99, v98, v97
	v_fma_f32 v100, -v96, v99, v98
	v_fmac_f32_e32 v99, v100, v97
	v_fma_f32 v98, -v96, v99, v98
	v_div_fmas_f32 v98, v98, v97, v99
	v_div_fixup_f32 v103, v98, v102, v2
	v_mov_b32_e32 v2, v103
	v_mul_f32_e32 v101, 0xbfb8aa3b, v3
	v_exp_f32_e32 v101, v101
	s_nop 0
	v_add_f32_e32 v102, 1.0, v101
	v_div_scale_f32 v96, s[34:35], v102, v102, v3
	v_rcp_f32_e32 v97, v96
	v_div_scale_f32 v98, vcc, v3, v102, v3
	v_fma_f32 v99, -v96, v97, 1.0
	v_fmac_f32_e32 v97, v99, v97
	v_mul_f32_e32 v99, v98, v97
	v_fma_f32 v100, -v96, v99, v98
	v_fmac_f32_e32 v99, v100, v97
	v_fma_f32 v98, -v96, v99, v98
	v_div_fmas_f32 v98, v98, v97, v99
	v_div_fixup_f32 v103, v98, v102, v3
	v_mov_b32_e32 v3, v103
	v_mul_f32_e32 v101, 0xbfb8aa3b, v4
	v_exp_f32_e32 v101, v101
	s_nop 0
	v_add_f32_e32 v102, 1.0, v101
	v_div_scale_f32 v96, s[34:35], v102, v102, v4
	v_rcp_f32_e32 v97, v96
	v_div_scale_f32 v98, vcc, v4, v102, v4
	v_fma_f32 v99, -v96, v97, 1.0
	v_fmac_f32_e32 v97, v99, v97
	v_mul_f32_e32 v99, v98, v97
	v_fma_f32 v100, -v96, v99, v98
	v_fmac_f32_e32 v99, v100, v97
	v_fma_f32 v98, -v96, v99, v98
	v_div_fmas_f32 v98, v98, v97, v99
	v_div_fixup_f32 v103, v98, v102, v4
	v_mov_b32_e32 v4, v103
	v_mul_f32_e32 v101, 0xbfb8aa3b, v5
	v_exp_f32_e32 v101, v101
	s_nop 0
	v_add_f32_e32 v102, 1.0, v101
	v_div_scale_f32 v96, s[34:35], v102, v102, v5
	v_rcp_f32_e32 v97, v96
	v_div_scale_f32 v98, vcc, v5, v102, v5
	v_fma_f32 v99, -v96, v97, 1.0
	v_fmac_f32_e32 v97, v99, v97
	v_mul_f32_e32 v99, v98, v97
	v_fma_f32 v100, -v96, v99, v98
	v_fmac_f32_e32 v99, v100, v97
	v_fma_f32 v98, -v96, v99, v98
	v_div_fmas_f32 v98, v98, v97, v99
	v_div_fixup_f32 v103, v98, v102, v5
	v_mov_b32_e32 v5, v103
	v_mul_f32_e32 v101, 0xbfb8aa3b, v6
	v_exp_f32_e32 v101, v101
	s_nop 0
	v_add_f32_e32 v102, 1.0, v101
	v_div_scale_f32 v96, s[34:35], v102, v102, v6
	v_rcp_f32_e32 v97, v96
	v_div_scale_f32 v98, vcc, v6, v102, v6
	v_fma_f32 v99, -v96, v97, 1.0
	v_fmac_f32_e32 v97, v99, v97
	v_mul_f32_e32 v99, v98, v97
	v_fma_f32 v100, -v96, v99, v98
	v_fmac_f32_e32 v99, v100, v97
	v_fma_f32 v98, -v96, v99, v98
	v_div_fmas_f32 v98, v98, v97, v99
	v_div_fixup_f32 v103, v98, v102, v6
	v_mov_b32_e32 v6, v103
	v_mul_f32_e32 v101, 0xbfb8aa3b, v7
	v_exp_f32_e32 v101, v101
	s_nop 0
	v_add_f32_e32 v102, 1.0, v101
	v_div_scale_f32 v96, s[34:35], v102, v102, v7
	v_rcp_f32_e32 v97, v96
	v_div_scale_f32 v98, vcc, v7, v102, v7
	v_fma_f32 v99, -v96, v97, 1.0
	v_fmac_f32_e32 v97, v99, v97
	v_mul_f32_e32 v99, v98, v97
	v_fma_f32 v100, -v96, v99, v98
	v_fmac_f32_e32 v99, v100, v97
	v_fma_f32 v98, -v96, v99, v98
	v_div_fmas_f32 v98, v98, v97, v99
	v_div_fixup_f32 v103, v98, v102, v7
	v_mov_b32_e32 v7, v103
	v_mul_f32_e32 v101, 0xbfb8aa3b, v8
	v_exp_f32_e32 v101, v101
	s_nop 0
	v_add_f32_e32 v102, 1.0, v101
	v_div_scale_f32 v96, s[34:35], v102, v102, v8
	v_rcp_f32_e32 v97, v96
	v_div_scale_f32 v98, vcc, v8, v102, v8
	v_fma_f32 v99, -v96, v97, 1.0
	v_fmac_f32_e32 v97, v99, v97
	v_mul_f32_e32 v99, v98, v97
	v_fma_f32 v100, -v96, v99, v98
	v_fmac_f32_e32 v99, v100, v97
	v_fma_f32 v98, -v96, v99, v98
	v_div_fmas_f32 v98, v98, v97, v99
	v_div_fixup_f32 v103, v98, v102, v8
	v_mov_b32_e32 v8, v103
	v_mul_f32_e32 v101, 0xbfb8aa3b, v9
	v_exp_f32_e32 v101, v101
	s_nop 0
	v_add_f32_e32 v102, 1.0, v101
	v_div_scale_f32 v96, s[34:35], v102, v102, v9
	v_rcp_f32_e32 v97, v96
	v_div_scale_f32 v98, vcc, v9, v102, v9
	v_fma_f32 v99, -v96, v97, 1.0
	v_fmac_f32_e32 v97, v99, v97
	v_mul_f32_e32 v99, v98, v97
	v_fma_f32 v100, -v96, v99, v98
	v_fmac_f32_e32 v99, v100, v97
	v_fma_f32 v98, -v96, v99, v98
	v_div_fmas_f32 v98, v98, v97, v99
	v_div_fixup_f32 v103, v98, v102, v9
	v_mov_b32_e32 v9, v103
	v_mul_f32_e32 v101, 0xbfb8aa3b, v240
	v_exp_f32_e32 v101, v101
	s_nop 0
	v_add_f32_e32 v102, 1.0, v101
	v_div_scale_f32 v96, s[34:35], v102, v102, v240
	v_rcp_f32_e32 v97, v96
	v_div_scale_f32 v98, vcc, v240, v102, v240
	v_fma_f32 v99, -v96, v97, 1.0
	v_fmac_f32_e32 v97, v99, v97
	v_mul_f32_e32 v99, v98, v97
	v_fma_f32 v100, -v96, v99, v98
	v_fmac_f32_e32 v99, v100, v97
	v_fma_f32 v98, -v96, v99, v98
	v_div_fmas_f32 v98, v98, v97, v99
	v_div_fixup_f32 v103, v98, v102, v240
	v_mov_b32_e32 v240, v103
	v_mul_f32_e32 v101, 0xbfb8aa3b, v241
	v_exp_f32_e32 v101, v101
	s_nop 0
	v_add_f32_e32 v102, 1.0, v101
	v_div_scale_f32 v96, s[34:35], v102, v102, v241
	v_rcp_f32_e32 v97, v96
	v_div_scale_f32 v98, vcc, v241, v102, v241
	v_fma_f32 v99, -v96, v97, 1.0
	v_fmac_f32_e32 v97, v99, v97
	v_mul_f32_e32 v99, v98, v97
	v_fma_f32 v100, -v96, v99, v98
	v_fmac_f32_e32 v99, v100, v97
	v_fma_f32 v98, -v96, v99, v98
; DI float bflo(unsigned d) { return __uint_as_float(d << 16); }
; DI float bfhi(unsigned d) { return __uint_as_float(d & 0xffff0000u); }
; DI float siluf(float x) { return x / (1.f + __expf(-x)); }
; DI void dn_prep(const Params& p, int item, char* smem) {
;     ...
;   for (int ps = 0; ps < 8; ++ps) {
;     const int combo = ps * 16 + (tid >> 4);
;     const int tt = combo & 63, part = combo >> 6, sub = tid & 15;
;     const int col = part * 512 + h * 128 + sub * 8;
;     float y[8] = {0.f, 0.f, 0.f, 0.f, 0.f, 0.f, 0.f, 0.f};
; #pragma unroll
;     for (int j = 0; j < 4; ++j) {
;       const int t = t0 + tt - 3 + j;
;       if (t >= 0) {
;         uint4 xv = *(const uint4*)&p.proj[(rowbase + t) * NP + col];
;         float4 wa = *(const float4*)&p.conv_w[j * 1536 + col], wb = *(const float4*)&p.conv_w[j * 1536 + col + 4];
;         y[0] += bflo(xv.x) * wa.x; y[1] += bfhi(xv.x) * wa.y; y[2] += bflo(xv.y) * wa.z; y[3] += bfhi(xv.y) * wa.w;
;         y[4] += bflo(xv.z) * wb.x; y[5] += bfhi(xv.z) * wb.y; y[6] += bflo(xv.w) * wb.z; y[7] += bfhi(xv.w) * wb.w;
;       }
;     }
;     float ss = 0.f;
; #pragma unroll
;     for (int e = 0; e < 8; ++e) { y[e] = siluf(y[e]); ss += y[e] * y[e]; }
	v_div_fmas_f32 v98, v98, v97, v99
	v_div_fixup_f32 v103, v98, v102, v241
	v_mov_b32_e32 v241, v103
	v_mul_f32_e32 v101, 0xbfb8aa3b, v242
	v_exp_f32_e32 v101, v101
	s_nop 0
	v_add_f32_e32 v102, 1.0, v101
	v_div_scale_f32 v96, s[34:35], v102, v102, v242
	v_rcp_f32_e32 v97, v96
	v_div_scale_f32 v98, vcc, v242, v102, v242
	v_fma_f32 v99, -v96, v97, 1.0
	v_fmac_f32_e32 v97, v99, v97
	v_mul_f32_e32 v99, v98, v97
	v_fma_f32 v100, -v96, v99, v98
	v_fmac_f32_e32 v99, v100, v97
	v_fma_f32 v98, -v96, v99, v98
	v_div_fmas_f32 v98, v98, v97, v99
	v_div_fixup_f32 v103, v98, v102, v242
	v_mov_b32_e32 v242, v103
	v_mul_f32_e32 v101, 0xbfb8aa3b, v243
	v_exp_f32_e32 v101, v101
	s_nop 0
	v_add_f32_e32 v102, 1.0, v101
	v_div_scale_f32 v96, s[34:35], v102, v102, v243
	v_rcp_f32_e32 v97, v96
	v_div_scale_f32 v98, vcc, v243, v102, v243
	v_fma_f32 v99, -v96, v97, 1.0
	v_fmac_f32_e32 v97, v99, v97
	v_mul_f32_e32 v99, v98, v97
	v_fma_f32 v100, -v96, v99, v98
	v_fmac_f32_e32 v99, v100, v97
	v_fma_f32 v98, -v96, v99, v98
	v_div_fmas_f32 v98, v98, v97, v99
	v_div_fixup_f32 v103, v98, v102, v243
	v_mov_b32_e32 v243, v103
	v_mul_f32_e32 v101, 0xbfb8aa3b, v244
	v_exp_f32_e32 v101, v101
	s_nop 0
	v_add_f32_e32 v102, 1.0, v101
	v_div_scale_f32 v96, s[34:35], v102, v102, v244
	v_rcp_f32_e32 v97, v96
	v_div_scale_f32 v98, vcc, v244, v102, v244
	v_fma_f32 v99, -v96, v97, 1.0
	v_fmac_f32_e32 v97, v99, v97
	v_mul_f32_e32 v99, v98, v97
	v_fma_f32 v100, -v96, v99, v98
	v_fmac_f32_e32 v99, v100, v97
	v_fma_f32 v98, -v96, v99, v98
	v_div_fmas_f32 v98, v98, v97, v99
	v_div_fixup_f32 v103, v98, v102, v244
	v_mov_b32_e32 v244, v103
	v_mul_f32_e32 v101, 0xbfb8aa3b, v245
	v_exp_f32_e32 v101, v101
	s_nop 0
	v_add_f32_e32 v102, 1.0, v101
	v_div_scale_f32 v96, s[34:35], v102, v102, v245
	v_rcp_f32_e32 v97, v96
	v_div_scale_f32 v98, vcc, v245, v102, v245
	v_fma_f32 v99, -v96, v97, 1.0
	v_fmac_f32_e32 v97, v99, v97
	v_mul_f32_e32 v99, v98, v97
	v_fma_f32 v100, -v96, v99, v98
	v_fmac_f32_e32 v99, v100, v97
	v_fma_f32 v98, -v96, v99, v98
	v_div_fmas_f32 v98, v98, v97, v99
	v_div_fixup_f32 v103, v98, v102, v245
	v_mov_b32_e32 v245, v103
	v_mul_f32_e32 v101, 0xbfb8aa3b, v246
	v_exp_f32_e32 v101, v101
	s_nop 0
	v_add_f32_e32 v102, 1.0, v101
	v_div_scale_f32 v96, s[34:35], v102, v102, v246
	v_rcp_f32_e32 v97, v96
	v_div_scale_f32 v98, vcc, v246, v102, v246
	v_fma_f32 v99, -v96, v97, 1.0
	v_fmac_f32_e32 v97, v99, v97
	v_mul_f32_e32 v99, v98, v97
	v_fma_f32 v100, -v96, v99, v98
	v_fmac_f32_e32 v99, v100, v97
	v_fma_f32 v98, -v96, v99, v98
	v_div_fmas_f32 v98, v98, v97, v99
	v_div_fixup_f32 v103, v98, v102, v246
	v_mov_b32_e32 v246, v103
	v_mul_f32_e32 v101, 0xbfb8aa3b, v247
	v_exp_f32_e32 v101, v101
	s_nop 0
	v_add_f32_e32 v102, 1.0, v101
	v_div_scale_f32 v96, s[34:35], v102, v102, v247
	v_rcp_f32_e32 v97, v96
	v_div_scale_f32 v98, vcc, v247, v102, v247
	v_fma_f32 v99, -v96, v97, 1.0
	v_fmac_f32_e32 v97, v99, v97
	v_mul_f32_e32 v99, v98, v97
	v_fma_f32 v100, -v96, v99, v98
	v_fmac_f32_e32 v99, v100, v97
	v_fma_f32 v98, -v96, v99, v98
	v_div_fmas_f32 v98, v98, v97, v99
	v_div_fixup_f32 v103, v98, v102, v247
	v_mov_b32_e32 v247, v103
	v_mul_f32_e32 v101, 0xbfb8aa3b, v248
	v_exp_f32_e32 v101, v101
	s_nop 0
	v_add_f32_e32 v102, 1.0, v101
	v_div_scale_f32 v96, s[34:35], v102, v102, v248
	v_rcp_f32_e32 v97, v96
	v_div_scale_f32 v98, vcc, v248, v102, v248
	v_fma_f32 v99, -v96, v97, 1.0
	v_fmac_f32_e32 v97, v99, v97
	v_mul_f32_e32 v99, v98, v97
	v_fma_f32 v100, -v96, v99, v98
	v_fmac_f32_e32 v99, v100, v97
	v_fma_f32 v98, -v96, v99, v98
	v_div_fmas_f32 v98, v98, v97, v99
	v_div_fixup_f32 v103, v98, v102, v248
	v_mov_b32_e32 v248, v103
	v_mul_f32_e32 v101, 0xbfb8aa3b, v249
	v_exp_f32_e32 v101, v101
	s_nop 0
	v_add_f32_e32 v102, 1.0, v101
	v_div_scale_f32 v96, s[34:35], v102, v102, v249
	v_rcp_f32_e32 v97, v96
	v_div_scale_f32 v98, vcc, v249, v102, v249
	v_fma_f32 v99, -v96, v97, 1.0
	v_fmac_f32_e32 v97, v99, v97
	v_mul_f32_e32 v99, v98, v97
	v_fma_f32 v100, -v96, v99, v98
	v_fmac_f32_e32 v99, v100, v97
	v_fma_f32 v98, -v96, v99, v98
	v_div_fmas_f32 v98, v98, v97, v99
	v_div_fixup_f32 v103, v98, v102, v249
	v_mov_b32_e32 v249, v103
	v_mul_f32_e32 v101, 0xbfb8aa3b, v250
	v_exp_f32_e32 v101, v101
	s_nop 0
	v_add_f32_e32 v102, 1.0, v101
	v_div_scale_f32 v96, s[34:35], v102, v102, v250
	v_rcp_f32_e32 v97, v96
	v_div_scale_f32 v98, vcc, v250, v102, v250
	v_fma_f32 v99, -v96, v97, 1.0
	v_fmac_f32_e32 v97, v99, v97
	v_mul_f32_e32 v99, v98, v97
	v_fma_f32 v100, -v96, v99, v98
	v_fmac_f32_e32 v99, v100, v97
	v_fma_f32 v98, -v96, v99, v98
	v_div_fmas_f32 v98, v98, v97, v99
	v_div_fixup_f32 v103, v98, v102, v250
	v_mov_b32_e32 v250, v103
	v_mul_f32_e32 v101, 0xbfb8aa3b, v251
	v_exp_f32_e32 v101, v101
	s_nop 0
	v_add_f32_e32 v102, 1.0, v101
	v_div_scale_f32 v96, s[34:35], v102, v102, v251
	v_rcp_f32_e32 v97, v96
	v_div_scale_f32 v98, vcc, v251, v102, v251
	v_fma_f32 v99, -v96, v97, 1.0
	v_fmac_f32_e32 v97, v99, v97
	v_mul_f32_e32 v99, v98, v97
	v_fma_f32 v100, -v96, v99, v98
	v_fmac_f32_e32 v99, v100, v97
	v_fma_f32 v98, -v96, v99, v98
	v_div_fmas_f32 v98, v98, v97, v99
	v_div_fixup_f32 v103, v98, v102, v251
	v_mov_b32_e32 v251, v103
	v_mul_f32_e32 v101, 0xbfb8aa3b, v252
	v_exp_f32_e32 v101, v101
	s_nop 0
	v_add_f32_e32 v102, 1.0, v101
	v_div_scale_f32 v96, s[34:35], v102, v102, v252
	v_rcp_f32_e32 v97, v96
	v_div_scale_f32 v98, vcc, v252, v102, v252
	v_fma_f32 v99, -v96, v97, 1.0
	v_fmac_f32_e32 v97, v99, v97
	v_mul_f32_e32 v99, v98, v97
	v_fma_f32 v100, -v96, v99, v98
	v_fmac_f32_e32 v99, v100, v97
	v_fma_f32 v98, -v96, v99, v98
	v_div_fmas_f32 v98, v98, v97, v99
	v_div_fixup_f32 v103, v98, v102, v252
; DI float siluf(float x) { return x / (1.f + __expf(-x)); }
; DI void dn_prep(const Params& p, int item, char* smem) {
;     ...
;     float ss = 0.f;
; #pragma unroll
;     for (int e = 0; e < 8; ++e) { y[e] = siluf(y[e]); ss += y[e] * y[e]; }
;     ss += __shfl_xor(ss, 1); ss += __shfl_xor(ss, 2); ss += __shfl_xor(ss, 4); ss += __shfl_xor(ss, 8);
;     float sc = rsqrtf(ss + EPS) * (part == 0 ? 0.08838834764831845f : 1.f);
	v_mov_b32_e32 v252, v103
	v_mul_f32_e32 v101, 0xbfb8aa3b, v253
	v_exp_f32_e32 v101, v101
	s_nop 0
	v_add_f32_e32 v102, 1.0, v101
	v_div_scale_f32 v96, s[34:35], v102, v102, v253
	v_rcp_f32_e32 v97, v96
	v_div_scale_f32 v98, vcc, v253, v102, v253
	v_fma_f32 v99, -v96, v97, 1.0
	v_fmac_f32_e32 v97, v99, v97
	v_mul_f32_e32 v99, v98, v97
	v_fma_f32 v100, -v96, v99, v98
	v_fmac_f32_e32 v99, v100, v97
	v_fma_f32 v98, -v96, v99, v98
	v_div_fmas_f32 v98, v98, v97, v99
	v_div_fixup_f32 v103, v98, v102, v253
	v_mov_b32_e32 v253, v103
	v_mul_f32_e32 v101, 0xbfb8aa3b, v254
	v_exp_f32_e32 v101, v101
	s_nop 0
	v_add_f32_e32 v102, 1.0, v101
	v_div_scale_f32 v96, s[34:35], v102, v102, v254
	v_rcp_f32_e32 v97, v96
	v_div_scale_f32 v98, vcc, v254, v102, v254
	v_fma_f32 v99, -v96, v97, 1.0
	v_fmac_f32_e32 v97, v99, v97
	v_mul_f32_e32 v99, v98, v97
	v_fma_f32 v100, -v96, v99, v98
	v_fmac_f32_e32 v99, v100, v97
	v_fma_f32 v98, -v96, v99, v98
	v_div_fmas_f32 v98, v98, v97, v99
	v_div_fixup_f32 v103, v98, v102, v254
	v_mov_b32_e32 v254, v103
	v_mul_f32_e32 v101, 0xbfb8aa3b, v61
	v_exp_f32_e32 v101, v101
	s_nop 0
	v_add_f32_e32 v102, 1.0, v101
	v_div_scale_f32 v96, s[34:35], v102, v102, v61
	v_rcp_f32_e32 v97, v96
	v_div_scale_f32 v98, vcc, v61, v102, v61
	v_fma_f32 v99, -v96, v97, 1.0
	v_fmac_f32_e32 v97, v99, v97
	v_mul_f32_e32 v99, v98, v97
	v_fma_f32 v100, -v96, v99, v98
	v_fmac_f32_e32 v99, v100, v97
	v_fma_f32 v98, -v96, v99, v98
	v_div_fmas_f32 v98, v98, v97, v99
	v_div_fixup_f32 v103, v98, v102, v61
	v_mov_b32_e32 v61, v103
	v_mul_f32_e32 v101, 0xbfb8aa3b, v71
	v_exp_f32_e32 v101, v101
	s_nop 0
	v_add_f32_e32 v102, 1.0, v101
	v_div_scale_f32 v96, s[34:35], v102, v102, v71
	v_rcp_f32_e32 v97, v96
	v_div_scale_f32 v98, vcc, v71, v102, v71
	v_fma_f32 v99, -v96, v97, 1.0
	v_fmac_f32_e32 v97, v99, v97
	v_mul_f32_e32 v99, v98, v97
	v_fma_f32 v100, -v96, v99, v98
	v_fmac_f32_e32 v99, v100, v97
	v_fma_f32 v98, -v96, v99, v98
	v_div_fmas_f32 v98, v98, v97, v99
	v_div_fixup_f32 v103, v98, v102, v71
	v_mov_b32_e32 v71, v103
	v_mul_f32_e32 v101, 0xbfb8aa3b, v73
	v_exp_f32_e32 v101, v101
	s_nop 0
	v_add_f32_e32 v102, 1.0, v101
	v_div_scale_f32 v96, s[34:35], v102, v102, v73
	v_rcp_f32_e32 v97, v96
	v_div_scale_f32 v98, vcc, v73, v102, v73
	v_fma_f32 v99, -v96, v97, 1.0
	v_fmac_f32_e32 v97, v99, v97
	v_mul_f32_e32 v99, v98, v97
	v_fma_f32 v100, -v96, v99, v98
	v_fmac_f32_e32 v99, v100, v97
	v_fma_f32 v98, -v96, v99, v98
	v_div_fmas_f32 v98, v98, v97, v99
	v_div_fixup_f32 v103, v98, v102, v73
	v_mov_b32_e32 v73, v103
	v_mul_f32_e32 v101, 0xbfb8aa3b, v88
	v_exp_f32_e32 v101, v101
	s_nop 0
	v_add_f32_e32 v102, 1.0, v101
	v_div_scale_f32 v96, s[34:35], v102, v102, v88
	v_rcp_f32_e32 v97, v96
	v_div_scale_f32 v98, vcc, v88, v102, v88
	v_fma_f32 v99, -v96, v97, 1.0
	v_fmac_f32_e32 v97, v99, v97
	v_mul_f32_e32 v99, v98, v97
	v_fma_f32 v100, -v96, v99, v98
	v_fmac_f32_e32 v99, v100, v97
	v_fma_f32 v98, -v96, v99, v98
	v_div_fmas_f32 v98, v98, v97, v99
	v_div_fixup_f32 v103, v98, v102, v88
	v_mov_b32_e32 v88, v103
	v_mul_f32_e32 v101, 0xbfb8aa3b, v90
	v_exp_f32_e32 v101, v101
	s_nop 0
	v_add_f32_e32 v102, 1.0, v101
	v_div_scale_f32 v96, s[34:35], v102, v102, v90
	v_rcp_f32_e32 v97, v96
	v_div_scale_f32 v98, vcc, v90, v102, v90
	v_fma_f32 v99, -v96, v97, 1.0
	v_fmac_f32_e32 v97, v99, v97
	v_mul_f32_e32 v99, v98, v97
	v_fma_f32 v100, -v96, v99, v98
	v_fmac_f32_e32 v99, v100, v97
	v_fma_f32 v98, -v96, v99, v98
	v_div_fmas_f32 v98, v98, v97, v99
	v_div_fixup_f32 v103, v98, v102, v90
	v_mov_b32_e32 v90, v103
	v_mul_f32_e32 v101, 0xbfb8aa3b, v92
	v_exp_f32_e32 v101, v101
	s_nop 0
	v_add_f32_e32 v102, 1.0, v101
	v_div_scale_f32 v96, s[34:35], v102, v102, v92
	v_rcp_f32_e32 v97, v96
	v_div_scale_f32 v98, vcc, v92, v102, v92
	v_fma_f32 v99, -v96, v97, 1.0
	v_fmac_f32_e32 v97, v99, v97
	v_mul_f32_e32 v99, v98, v97
	v_fma_f32 v100, -v96, v99, v98
	v_fmac_f32_e32 v99, v100, v97
	v_fma_f32 v98, -v96, v99, v98
	v_div_fmas_f32 v98, v98, v97, v99
	v_div_fixup_f32 v103, v98, v102, v92
	v_mov_b32_e32 v92, v103
	v_mul_f32_e32 v101, 0xbfb8aa3b, v94
	v_exp_f32_e32 v101, v101
	s_nop 0
	v_add_f32_e32 v102, 1.0, v101
	v_div_scale_f32 v96, s[34:35], v102, v102, v94
	v_rcp_f32_e32 v97, v96
	v_div_scale_f32 v98, vcc, v94, v102, v94
	v_fma_f32 v99, -v96, v97, 1.0
	v_fmac_f32_e32 v97, v99, v97
	v_mul_f32_e32 v99, v98, v97
	v_fma_f32 v100, -v96, v99, v98
	v_fmac_f32_e32 v99, v100, v97
	v_fma_f32 v98, -v96, v99, v98
	v_div_fmas_f32 v98, v98, v97, v99
	v_div_fixup_f32 v103, v98, v102, v94
	v_mov_b32_e32 v94, v103
	v_mul_f32_e32 v101, 0xbfb8aa3b, v194
	v_exp_f32_e32 v101, v101
	s_nop 0
	v_add_f32_e32 v102, 1.0, v101
	v_div_scale_f32 v96, s[34:35], v102, v102, v194
	v_rcp_f32_e32 v97, v96
	v_div_scale_f32 v98, vcc, v194, v102, v194
	v_fma_f32 v99, -v96, v97, 1.0
	v_fmac_f32_e32 v97, v99, v97
	v_mul_f32_e32 v99, v98, v97
	v_fma_f32 v100, -v96, v99, v98
	v_fmac_f32_e32 v99, v100, v97
	v_fma_f32 v98, -v96, v99, v98
	v_div_fmas_f32 v98, v98, v97, v99
	v_div_fixup_f32 v103, v98, v102, v194
	v_mov_b32_e32 v194, v103
	v_mul_f32_e32 v104, v1, v1
	v_fmac_f32_e32 v104, v2, v2
	v_fmac_f32_e32 v104, v3, v3
	v_fmac_f32_e32 v104, v4, v4
	v_fmac_f32_e32 v104, v5, v5
	v_fmac_f32_e32 v104, v6, v6
	v_fmac_f32_e32 v104, v7, v7
	v_fmac_f32_e32 v104, v8, v8
	v_mul_f32_e32 v105, v9, v9
	v_fmac_f32_e32 v105, v240, v240
	v_fmac_f32_e32 v105, v241, v241
	v_fmac_f32_e32 v105, v242, v242
	v_fmac_f32_e32 v105, v243, v243
	v_fmac_f32_e32 v105, v244, v244
	v_fmac_f32_e32 v105, v245, v245
	v_fmac_f32_e32 v105, v246, v246
	v_mul_f32_e32 v106, v247, v247
	v_fmac_f32_e32 v106, v248, v248
	v_fmac_f32_e32 v106, v249, v249
	v_fmac_f32_e32 v106, v250, v250
	v_fmac_f32_e32 v106, v251, v251
	v_fmac_f32_e32 v106, v252, v252
	v_fmac_f32_e32 v106, v253, v253
	v_fmac_f32_e32 v106, v254, v254
	v_mul_f32_e32 v107, v61, v61
	v_fmac_f32_e32 v107, v71, v71
	v_fmac_f32_e32 v107, v73, v73
	v_fmac_f32_e32 v107, v88, v88
	v_fmac_f32_e32 v107, v90, v90
	v_fmac_f32_e32 v107, v92, v92
	v_fmac_f32_e32 v107, v94, v94
	v_fmac_f32_e32 v107, v194, v194
	v_and_b32_e32 v112, 63, v142
	v_xor_b32_e32 v113, 1, v112
	v_lshlrev_b32_e32 v113, 2, v113
	v_xor_b32_e32 v114, 2, v112
	v_lshlrev_b32_e32 v114, 2, v114
	v_xor_b32_e32 v115, 4, v112
	v_lshlrev_b32_e32 v115, 2, v115
	v_xor_b32_e32 v116, 8, v112
	v_lshlrev_b32_e32 v116, 2, v116
	ds_bpermute_b32 v108, v113, v104
	ds_bpermute_b32 v109, v113, v105
	ds_bpermute_b32 v110, v113, v106
	ds_bpermute_b32 v111, v113, v107
	s_waitcnt lgkmcnt(0)
; DI unsigned pack2(float a, float b) { return (unsigned)f2bf(a) | ((unsigned)f2bf(b) << 16); }
; DI void dn_prep(const Params& p, int item, char* smem) {
;     ...
;     ss += __shfl_xor(ss, 1); ss += __shfl_xor(ss, 2); ss += __shfl_xor(ss, 4); ss += __shfl_xor(ss, 8);
;     float sc = rsqrtf(ss + EPS) * (part == 0 ? 0.08838834764831845f : 1.f);
;     uint4 o; o.x = pack2(y[0] * sc, y[1] * sc); o.y = pack2(y[2] * sc, y[3] * sc); o.z = pack2(y[4] * sc, y[5] * sc); o.w = pack2(y[6] * sc, y[7] * sc);
;     *(uint4*)&((part == 0 ? qs : ksm)[tt * 136 + sub * 8]) = o;
	v_add_f32_e32 v104, v104, v108
	v_add_f32_e32 v105, v105, v109
	v_add_f32_e32 v106, v106, v110
	v_add_f32_e32 v107, v107, v111
	ds_bpermute_b32 v108, v114, v104
	ds_bpermute_b32 v109, v114, v105
	ds_bpermute_b32 v110, v114, v106
	ds_bpermute_b32 v111, v114, v107
	s_waitcnt lgkmcnt(0)
	v_add_f32_e32 v104, v104, v108
	v_add_f32_e32 v105, v105, v109
	v_add_f32_e32 v106, v106, v110
	v_add_f32_e32 v107, v107, v111
	ds_bpermute_b32 v108, v115, v104
	ds_bpermute_b32 v109, v115, v105
	ds_bpermute_b32 v110, v115, v106
	ds_bpermute_b32 v111, v115, v107
	s_waitcnt lgkmcnt(0)
	v_add_f32_e32 v104, v104, v108
	v_add_f32_e32 v105, v105, v109
	v_add_f32_e32 v106, v106, v110
	v_add_f32_e32 v107, v107, v111
	ds_bpermute_b32 v108, v116, v104
	ds_bpermute_b32 v109, v116, v105
	ds_bpermute_b32 v110, v116, v106
	ds_bpermute_b32 v111, v116, v107
	s_waitcnt lgkmcnt(0)
	v_add_f32_e32 v104, v104, v108
	v_add_f32_e32 v105, v105, v109
	v_add_f32_e32 v106, v106, v110
	v_add_f32_e32 v107, v107, v111
	v_add_f32_e32 v104, 0x358637bd, v104
	v_cmp_gt_f32_e32 vcc, 0x800000, v104
	v_mul_f32_e32 v108, 0x4b800000, v104
	s_nop 0
	v_cndmask_b32_e32 v104, v104, v108, vcc
	v_rsq_f32_e32 v104, v104
	s_nop 0
	v_mul_f32_e32 v108, 0x45800000, v104
	v_cndmask_b32_e32 v104, v104, v108, vcc
	v_add_f32_e32 v105, 0x358637bd, v105
	v_cmp_gt_f32_e32 vcc, 0x800000, v105
	v_mul_f32_e32 v109, 0x4b800000, v105
	s_nop 0
	v_cndmask_b32_e32 v105, v105, v109, vcc
	v_rsq_f32_e32 v105, v105
	s_nop 0
	v_mul_f32_e32 v109, 0x45800000, v105
	v_cndmask_b32_e32 v105, v105, v109, vcc
	v_add_f32_e32 v106, 0x358637bd, v106
	v_cmp_gt_f32_e32 vcc, 0x800000, v106
	v_mul_f32_e32 v110, 0x4b800000, v106
	s_nop 0
	v_cndmask_b32_e32 v106, v106, v110, vcc
	v_rsq_f32_e32 v106, v106
	s_nop 0
	v_mul_f32_e32 v110, 0x45800000, v106
	v_cndmask_b32_e32 v106, v106, v110, vcc
	v_add_f32_e32 v107, 0x358637bd, v107
	v_cmp_gt_f32_e32 vcc, 0x800000, v107
	v_mul_f32_e32 v111, 0x4b800000, v107
	s_nop 0
	v_cndmask_b32_e32 v107, v107, v111, vcc
	v_rsq_f32_e32 v107, v107
	s_nop 0
	v_mul_f32_e32 v111, 0x45800000, v107
	v_cndmask_b32_e32 v107, v107, v111, vcc
	s_movk_i32 s34, 0x7fff
	s_mov_b32 s35, 0x7060302
	v_lshrrev_b32_e32 v118, 4, v142
	v_and_b32_e32 v119, 15, v142
	v_mul_u32_u24_e32 v117, 0x110, v118
	v_lshl_add_u32 v117, v119, 4, v117
	v_mul_f32_e32 v1, v1, v104
	v_bfe_u32 v108, v1, 16, 1
	v_add3_u32 v1, v1, v108, s34
	v_mul_f32_e32 v2, v2, v104
	v_bfe_u32 v108, v2, 16, 1
	v_add3_u32 v2, v2, v108, s34
	v_mul_f32_e32 v3, v3, v104
	v_bfe_u32 v108, v3, 16, 1
	v_add3_u32 v3, v3, v108, s34
	v_mul_f32_e32 v4, v4, v104
	v_bfe_u32 v108, v4, 16, 1
	v_add3_u32 v4, v4, v108, s34
	v_mul_f32_e32 v5, v5, v104
	v_bfe_u32 v108, v5, 16, 1
	v_add3_u32 v5, v5, v108, s34
	v_mul_f32_e32 v6, v6, v104
	v_bfe_u32 v108, v6, 16, 1
	v_add3_u32 v6, v6, v108, s34
	v_mul_f32_e32 v7, v7, v104
	v_bfe_u32 v108, v7, 16, 1
	v_add3_u32 v7, v7, v108, s34
	v_mul_f32_e32 v8, v8, v104
	v_bfe_u32 v108, v8, 16, 1
	v_add3_u32 v8, v8, v108, s34
	v_perm_b32 v120, v2, v1, s35
	v_perm_b32 v121, v4, v3, s35
	v_perm_b32 v122, v6, v5, s35
	v_perm_b32 v123, v8, v7, s35
	ds_write_b128 v117, v[120:123] offset:17408
	s_nop 0
	v_mul_f32_e32 v9, v9, v105
	v_bfe_u32 v108, v9, 16, 1
	v_add3_u32 v9, v9, v108, s34
	v_mul_f32_e32 v240, v240, v105
	v_bfe_u32 v108, v240, 16, 1
	v_add3_u32 v240, v240, v108, s34
	v_mul_f32_e32 v241, v241, v105
	v_bfe_u32 v108, v241, 16, 1
	v_add3_u32 v241, v241, v108, s34
	v_mul_f32_e32 v242, v242, v105
	v_bfe_u32 v108, v242, 16, 1
	v_add3_u32 v242, v242, v108, s34
	v_mul_f32_e32 v243, v243, v105
	v_bfe_u32 v108, v243, 16, 1
	v_add3_u32 v243, v243, v108, s34
	v_mul_f32_e32 v244, v244, v105
	v_bfe_u32 v108, v244, 16, 1
	v_add3_u32 v244, v244, v108, s34
	v_mul_f32_e32 v245, v245, v105
	v_bfe_u32 v108, v245, 16, 1
	v_add3_u32 v245, v245, v108, s34
	v_mul_f32_e32 v246, v246, v105
	v_bfe_u32 v108, v246, 16, 1
	v_add3_u32 v246, v246, v108, s34
	v_perm_b32 v120, v240, v9, s35
	v_perm_b32 v121, v242, v241, s35
	v_perm_b32 v122, v244, v243, s35
	v_perm_b32 v123, v246, v245, s35
	ds_write_b128 v117, v[120:123] offset:21760
	s_nop 0
	v_mul_f32_e32 v247, v247, v106
	v_bfe_u32 v108, v247, 16, 1
	v_add3_u32 v247, v247, v108, s34
	v_mul_f32_e32 v248, v248, v106
	v_bfe_u32 v108, v248, 16, 1
	v_add3_u32 v248, v248, v108, s34
	v_mul_f32_e32 v249, v249, v106
	v_bfe_u32 v108, v249, 16, 1
	v_add3_u32 v249, v249, v108, s34
	v_mul_f32_e32 v250, v250, v106
	v_bfe_u32 v108, v250, 16, 1
	v_add3_u32 v250, v250, v108, s34
	v_mul_f32_e32 v251, v251, v106
	v_bfe_u32 v108, v251, 16, 1
	v_add3_u32 v251, v251, v108, s34
	v_mul_f32_e32 v252, v252, v106
	v_bfe_u32 v108, v252, 16, 1
	v_add3_u32 v252, v252, v108, s34
	v_mul_f32_e32 v253, v253, v106
	v_bfe_u32 v108, v253, 16, 1
	v_add3_u32 v253, v253, v108, s34
	v_mul_f32_e32 v254, v254, v106
	v_bfe_u32 v108, v254, 16, 1
	v_add3_u32 v254, v254, v108, s34
	v_perm_b32 v120, v248, v247, s35
	v_perm_b32 v121, v250, v249, s35
	v_perm_b32 v122, v252, v251, s35
	v_perm_b32 v123, v254, v253, s35
	ds_write_b128 v117, v[120:123] offset:26112
	s_nop 0
	v_mul_f32_e32 v61, v61, v107
	v_bfe_u32 v108, v61, 16, 1
	v_add3_u32 v61, v61, v108, s34
	v_mul_f32_e32 v71, v71, v107
	v_bfe_u32 v108, v71, 16, 1
	v_add3_u32 v71, v71, v108, s34
	v_mul_f32_e32 v73, v73, v107
	v_bfe_u32 v108, v73, 16, 1
	v_add3_u32 v73, v73, v108, s34
	v_mul_f32_e32 v88, v88, v107
	v_bfe_u32 v108, v88, 16, 1
	v_add3_u32 v88, v88, v108, s34
	v_mul_f32_e32 v90, v90, v107
	v_bfe_u32 v108, v90, 16, 1
	v_add3_u32 v90, v90, v108, s34
	v_mul_f32_e32 v92, v92, v107
	v_bfe_u32 v108, v92, 16, 1
	v_add3_u32 v92, v92, v108, s34
	v_mul_f32_e32 v94, v94, v107
	v_bfe_u32 v108, v94, 16, 1
	v_add3_u32 v94, v94, v108, s34
	v_mul_f32_e32 v194, v194, v107
	v_bfe_u32 v108, v194, 16, 1
	v_add3_u32 v194, v194, v108, s34
	v_perm_b32 v120, v71, v61, s35
	v_perm_b32 v121, v88, v73, s35
	v_perm_b32 v122, v92, v90, s35
	v_perm_b32 v123, v194, v94, s35
	ds_write_b128 v117, v[120:123] offset:30464
	s_nop 0

; DI unsigned pack2(float a, float b) { return (unsigned)f2bf(a) | ((unsigned)f2bf(b) << 16); }
; DI float bflo(unsigned d) { return __uint_as_float(d << 16); }
; DI float bfhi(unsigned d) { return __uint_as_float(d & 0xffff0000u); }
; DI float siluf(float x) { return x / (1.f + __expf(-x)); }
; DI void phase4(const Params& p) {
;   const int lane = threadIdx.x & 63, w = threadIdx.x >> 6;
;   for (int row = blockIdx.x * 4 + w; row < MT; row += gridDim.x * 4) {
;     u16* dst = p.Amix + (size_t)row * 768;
; #pragma unroll
;     for (int h = 0; h < 4; ++h) {
;       unsigned ov = *(const unsigned*)&p.odn[(size_t)row * 512 + h * 128 + lane * 2];
;       unsigned zv = *(const unsigned*)&p.proj[(size_t)row * NP + 1536 + h * 128 + lane * 2];
;       float o0 = bflo(ov), o1 = bfhi(ov);
;       float ss = wave_sum(o0 * o0 + o1 * o1);
;       float rs = rsqrtf(ss * (1.f / 128.f) + EPS);
;       float2 gn = *(const float2*)&p.g_onorm[lane * 2];
;       float y0 = o0 * rs * gn.x * siluf(bflo(zv)), y1 = o1 * rs * gn.y * siluf(bfhi(zv));
;       *(unsigned*)&dst[h * 128 + lane * 2] = pack2(y0, y1);
;     }
;     {
;       const int h = lane >> 4;
;       float l0 = p.lse[((size_t)0 * MT + row) * 4 + h], l1 = p.lse[((size_t)1 * MT + row) * 4 + h], l2 = p.lse[((size_t)2 * MT + row) * 4 + h];
;       float m = fmaxf(l0, fmaxf(l1, l2));
;       float e0 = __expf(l0 - m), e1 = __expf(l1 - m), e2 = __expf(l2 - m);
;       float inv = 1.f / (e0 + e1 + e2);
;       uint2 a = *(const uint2*)&p.osw[((size_t)0 * MT + row) * 256 + lane * 4];
;       uint2 c = *(const uint2*)&p.osw[((size_t)1 * MT + row) * 256 + lane * 4];
;       uint2 d = *(const uint2*)&p.osw[((size_t)2 * MT + row) * 256 + lane * 4];
.LBB0_669:
	s_or_b64 exec, exec, s[2:3]
	s_mov_b32 s0, 0x8080
	v_cmp_gt_i32_e64 s[8:9], s0, v163
	v_mov_b32_e32 v93, 0
	v_lshlrev_b32_e32 v92, 1, v144
	s_waitcnt lgkmcnt(0)
	s_barrier
	s_and_saveexec_b64 s[2:3], s[8:9]
	s_cbranch_execz .LBB0_672
	v_readfirstlane_b32 s10, v163
	v_mbcnt_lo_u32_b32 v0, -1, 0
	v_mbcnt_hi_u32_b32 v0, -1, v0
	v_mov_b32_e32 v20, 0x101d0
	v_mov_b32_e32 v21, 0x101c8
	v_mov_b32_e32 v22, 0x101e0
	v_mov_b32_e32 v23, 0x10160
	v_mov_b32_e32 v24, 0x10070
	ds_read_b128 v[72:75], v20
	ds_read_b64 v[76:77], v21
	ds_read_b64 v[78:79], v22
	ds_read_b64 v[80:81], v23
	ds_read_b64 v[82:83], v24
	v_lshlrev_b32_e32 v1, 2, v0
	v_lshlrev_b32_e32 v2, 3, v0
	v_lshrrev_b32_e32 v3, 4, v0
	v_lshlrev_b32_e32 v3, 2, v3
	v_add_u32_e32 v4, 0x80800, v3
	v_add_u32_e32 v5, 0x101000, v3
	v_mov_b32_e32 v6, v2
	v_add_u32_e32 v7, 0x1010000, v2
	v_add_u32_e32 v8, 0x2020000, v2
	v_mov_b32_e32 v9, 0x358637bd
	v_xor_b32_e32 v12, 32, v0
	v_lshlrev_b32_e32 v12, 2, v12
	v_xor_b32_e32 v13, 16, v0
	v_lshlrev_b32_e32 v13, 2, v13
	v_xor_b32_e32 v14, 8, v0
	v_lshlrev_b32_e32 v14, 2, v14
	v_xor_b32_e32 v15, 4, v0
	v_lshlrev_b32_e32 v15, 2, v15
	v_xor_b32_e32 v16, 2, v0
	v_lshlrev_b32_e32 v16, 2, v16
	v_xor_b32_e32 v17, 1, v0
	v_lshlrev_b32_e32 v17, 2, v17
	s_waitcnt lgkmcnt(0)
	v_readfirstlane_b32 s12, v72
	v_readfirstlane_b32 s13, v73
	v_readfirstlane_b32 s14, v74
	v_readfirstlane_b32 s15, v75
	v_readfirstlane_b32 s16, v76
	v_readfirstlane_b32 s17, v77
	v_readfirstlane_b32 s18, v78
	v_readfirstlane_b32 s19, v79
	v_readfirstlane_b32 s20, v80
	v_readfirstlane_b32 s21, v81
	v_readfirstlane_b32 s88, v82
	v_readfirstlane_b32 s89, v83
	s_mov_b32 s1, 0xffff0000
	s_movk_i32 s23, 0x7fff
	s_nop 3
	global_load_dwordx2 v[18:19], v2, s[88:89]
	s_mov_b32 s11, 1
	s_lshl_b32 s0, s10, 10
	s_add_u32 s92, s12, s0
	s_addc_u32 s93, s13, 0
	s_mul_i32 s0, s10, 0x2200
	s_add_u32 s0, s0, 0xc00
	s_add_u32 s94, s20, s0
	s_addc_u32 s95, s21, 0
	s_lshl_b32 s0, s10, 4
	s_add_u32 s96, s18, s0
	s_addc_u32 s97, s19, 0
	s_lshl_b32 s0, s10, 9
	s_add_u32 s90, s16, s0
	s_addc_u32 s91, s17, 0
	global_load_dword v32, v1, s[92:93] offset:0
	global_load_dword v33, v1, s[92:93] offset:256
	global_load_dword v34, v1, s[92:93] offset:512
	global_load_dword v35, v1, s[92:93] offset:768
	global_load_dword v36, v1, s[94:95] offset:0
	global_load_dword v37, v1, s[94:95] offset:256
	global_load_dword v38, v1, s[94:95] offset:512
	global_load_dword v39, v1, s[94:95] offset:768
	global_load_dword v40, v3, s[96:97]
	global_load_dword v41, v4, s[96:97]
	global_load_dword v42, v5, s[96:97]
	global_load_dwordx2 v[44:45], v6, s[90:91]
	global_load_dwordx2 v[46:47], v7, s[90:91]
	global_load_dwordx2 v[48:49], v8, s[90:91]
.Lp4_loop:
	s_add_i32 s22, s10, s78
	s_cmp_lt_i32 s22, 0x8080
	s_cbranch_scc0 .Lp4_lastA
	s_lshl_b32 s0, s22, 10
	s_add_u32 s92, s12, s0
	s_addc_u32 s93, s13, 0
	s_mul_i32 s0, s22, 0x2200
	s_add_u32 s0, s0, 0xc00
	s_add_u32 s94, s20, s0
	s_addc_u32 s95, s21, 0
	s_lshl_b32 s0, s22, 4
	s_add_u32 s96, s18, s0
	s_addc_u32 s97, s19, 0
	s_lshl_b32 s0, s22, 9
	s_add_u32 s90, s16, s0
	s_addc_u32 s91, s17, 0
	global_load_dword v52, v1, s[92:93] offset:0
	global_load_dword v53, v1, s[92:93] offset:256
	global_load_dword v54, v1, s[92:93] offset:512
	global_load_dword v55, v1, s[92:93] offset:768
	global_load_dword v56, v1, s[94:95] offset:0
	global_load_dword v57, v1, s[94:95] offset:256
	global_load_dword v58, v1, s[94:95] offset:512
	global_load_dword v59, v1, s[94:95] offset:768
	global_load_dword v60, v3, s[96:97]
	global_load_dword v61, v4, s[96:97]
	global_load_dword v62, v5, s[96:97]
	global_load_dwordx2 v[64:65], v6, s[90:91]
	global_load_dwordx2 v[66:67], v7, s[90:91]
	global_load_dwordx2 v[68:69], v8, s[90:91]
	s_cmp_eq_u32 s11, 1
	s_cbranch_scc1 .Lp4_w14
	s_waitcnt vmcnt(19)
	s_branch .Lp4_goA
.Lp4_w14:
	s_waitcnt vmcnt(14)
	s_branch .Lp4_goA

; DI float bflo(unsigned d) { return __uint_as_float(d << 16); }
; DI float bfhi(unsigned d) { return __uint_as_float(d & 0xffff0000u); }
; DI float siluf(float x) { return x / (1.f + __expf(-x)); }
; DI void phase4(const Params& p) {
;     ...
;     for (int h = 0; h < 4; ++h) {
;       unsigned ov = *(const unsigned*)&p.odn[(size_t)row * 512 + h * 128 + lane * 2];
;       unsigned zv = *(const unsigned*)&p.proj[(size_t)row * NP + 1536 + h * 128 + lane * 2];
;       float o0 = bflo(ov), o1 = bfhi(ov);
;       float ss = wave_sum(o0 * o0 + o1 * o1);
;       float rs = rsqrtf(ss * (1.f / 128.f) + EPS);
;       float2 gn = *(const float2*)&p.g_onorm[lane * 2];
;       float y0 = o0 * rs * gn.x * siluf(bflo(zv)), y1 = o1 * rs * gn.y * siluf(bfhi(zv));
.Lp4_goA:
	s_mov_b32 s11, 0
	v_lshlrev_b32_e32 v72, 16, v32
	v_and_b32_e32 v76, 0xffff0000, v32
	v_lshlrev_b32_e32 v80, 16, v36
	v_and_b32_e32 v84, 0xffff0000, v36
	v_mul_f32_e32 v88, v72, v72
	v_mul_f32_e32 v92, v76, v76
	v_add_f32_e32 v88, v88, v92
	v_lshlrev_b32_e32 v73, 16, v33
	v_and_b32_e32 v77, 0xffff0000, v33
	v_lshlrev_b32_e32 v81, 16, v37
	v_and_b32_e32 v85, 0xffff0000, v37
	v_mul_f32_e32 v89, v73, v73
	v_mul_f32_e32 v93, v77, v77
	v_add_f32_e32 v89, v89, v93
	v_lshlrev_b32_e32 v74, 16, v34
	v_and_b32_e32 v78, 0xffff0000, v34
	v_lshlrev_b32_e32 v82, 16, v38
	v_and_b32_e32 v86, 0xffff0000, v38
	v_mul_f32_e32 v90, v74, v74
	v_mul_f32_e32 v94, v78, v78
	v_add_f32_e32 v90, v90, v94
	v_lshlrev_b32_e32 v75, 16, v35
	v_and_b32_e32 v79, 0xffff0000, v35
	v_lshlrev_b32_e32 v83, 16, v39
	v_and_b32_e32 v87, 0xffff0000, v39
	v_mul_f32_e32 v91, v75, v75
	v_mul_f32_e32 v95, v79, v79
	v_add_f32_e32 v91, v91, v95
	ds_bpermute_b32 v92, v12, v88
	ds_bpermute_b32 v93, v12, v89
	ds_bpermute_b32 v94, v12, v90
	ds_bpermute_b32 v95, v12, v91
	s_waitcnt lgkmcnt(0)
	v_add_f32_e32 v88, v88, v92
	v_add_f32_e32 v89, v89, v93
	v_add_f32_e32 v90, v90, v94
	v_add_f32_e32 v91, v91, v95
	ds_bpermute_b32 v92, v13, v88
	ds_bpermute_b32 v93, v13, v89
	ds_bpermute_b32 v94, v13, v90
	ds_bpermute_b32 v95, v13, v91
	s_waitcnt lgkmcnt(0)
	v_add_f32_e32 v88, v88, v92
	v_add_f32_e32 v89, v89, v93
	v_add_f32_e32 v90, v90, v94
	v_add_f32_e32 v91, v91, v95
	ds_bpermute_b32 v92, v14, v88
	ds_bpermute_b32 v93, v14, v89
	ds_bpermute_b32 v94, v14, v90
	ds_bpermute_b32 v95, v14, v91
	s_waitcnt lgkmcnt(0)
	v_add_f32_e32 v88, v88, v92
	v_add_f32_e32 v89, v89, v93
	v_add_f32_e32 v90, v90, v94
	v_add_f32_e32 v91, v91, v95
	ds_bpermute_b32 v92, v15, v88
	ds_bpermute_b32 v93, v15, v89
	ds_bpermute_b32 v94, v15, v90
	ds_bpermute_b32 v95, v15, v91
	s_waitcnt lgkmcnt(0)
	v_add_f32_e32 v88, v88, v92
	v_add_f32_e32 v89, v89, v93
	v_add_f32_e32 v90, v90, v94
	v_add_f32_e32 v91, v91, v95
	ds_bpermute_b32 v92, v16, v88
	ds_bpermute_b32 v93, v16, v89
	ds_bpermute_b32 v94, v16, v90
	ds_bpermute_b32 v95, v16, v91
	s_waitcnt lgkmcnt(0)
	v_add_f32_e32 v88, v88, v92
	v_add_f32_e32 v89, v89, v93
	v_add_f32_e32 v90, v90, v94
	v_add_f32_e32 v91, v91, v95
	ds_bpermute_b32 v92, v17, v88
	ds_bpermute_b32 v93, v17, v89
	ds_bpermute_b32 v94, v17, v90
	ds_bpermute_b32 v95, v17, v91
	s_waitcnt lgkmcnt(0)
	v_add_f32_e32 v88, v88, v92
	v_add_f32_e32 v89, v89, v93
	v_add_f32_e32 v90, v90, v94
	v_add_f32_e32 v91, v91, v95
	v_mul_f32_e32 v109, 0xbfb8aa3b, v80
	v_exp_f32_e32 v109, v109
	s_nop 0
	v_add_f32_e32 v110, 1.0, v109
	v_div_scale_f32 v104, s[96:97], v110, v110, v80
	v_rcp_f32_e32 v105, v104
	v_div_scale_f32 v106, vcc, v80, v110, v80
	v_fma_f32 v107, -v104, v105, 1.0
	v_fmac_f32_e32 v105, v107, v105
	v_mul_f32_e32 v107, v106, v105
	v_fma_f32 v108, -v104, v107, v106
	v_fmac_f32_e32 v107, v108, v105
	v_fma_f32 v106, -v104, v107, v106
	v_div_fmas_f32 v106, v106, v105, v107
	v_div_fixup_f32 v96, v106, v110, v80
	v_mul_f32_e32 v109, 0xbfb8aa3b, v84
	v_exp_f32_e32 v109, v109
	s_nop 0
	v_add_f32_e32 v110, 1.0, v109
	v_div_scale_f32 v104, s[96:97], v110, v110, v84
	v_rcp_f32_e32 v105, v104
	v_div_scale_f32 v106, vcc, v84, v110, v84
	v_fma_f32 v107, -v104, v105, 1.0
	v_fmac_f32_e32 v105, v107, v105
	v_mul_f32_e32 v107, v106, v105
	v_fma_f32 v108, -v104, v107, v106
	v_fmac_f32_e32 v107, v108, v105
	v_fma_f32 v106, -v104, v107, v106
	v_div_fmas_f32 v106, v106, v105, v107
	v_div_fixup_f32 v100, v106, v110, v84
	v_mul_f32_e32 v109, 0xbfb8aa3b, v81
	v_exp_f32_e32 v109, v109
	s_nop 0
	v_add_f32_e32 v110, 1.0, v109
	v_div_scale_f32 v104, s[96:97], v110, v110, v81
	v_rcp_f32_e32 v105, v104
	v_div_scale_f32 v106, vcc, v81, v110, v81
	v_fma_f32 v107, -v104, v105, 1.0
	v_fmac_f32_e32 v105, v107, v105
	v_mul_f32_e32 v107, v106, v105
	v_fma_f32 v108, -v104, v107, v106
	v_fmac_f32_e32 v107, v108, v105
	v_fma_f32 v106, -v104, v107, v106
	v_div_fmas_f32 v106, v106, v105, v107
	v_div_fixup_f32 v97, v106, v110, v81
	v_mul_f32_e32 v109, 0xbfb8aa3b, v85
	v_exp_f32_e32 v109, v109
	s_nop 0
	v_add_f32_e32 v110, 1.0, v109
	v_div_scale_f32 v104, s[96:97], v110, v110, v85
	v_rcp_f32_e32 v105, v104
	v_div_scale_f32 v106, vcc, v85, v110, v85
	v_fma_f32 v107, -v104, v105, 1.0
	v_fmac_f32_e32 v105, v107, v105
	v_mul_f32_e32 v107, v106, v105
	v_fma_f32 v108, -v104, v107, v106
	v_fmac_f32_e32 v107, v108, v105
	v_fma_f32 v106, -v104, v107, v106
	v_div_fmas_f32 v106, v106, v105, v107
	v_div_fixup_f32 v101, v106, v110, v85
	v_mul_f32_e32 v109, 0xbfb8aa3b, v82
	v_exp_f32_e32 v109, v109
	s_nop 0
	v_add_f32_e32 v110, 1.0, v109
	v_div_scale_f32 v104, s[96:97], v110, v110, v82
	v_rcp_f32_e32 v105, v104
	v_div_scale_f32 v106, vcc, v82, v110, v82
	v_fma_f32 v107, -v104, v105, 1.0
	v_fmac_f32_e32 v105, v107, v105
	v_mul_f32_e32 v107, v106, v105
	v_fma_f32 v108, -v104, v107, v106
	v_fmac_f32_e32 v107, v108, v105
	v_fma_f32 v106, -v104, v107, v106
	v_div_fmas_f32 v106, v106, v105, v107
	v_div_fixup_f32 v98, v106, v110, v82
	v_mul_f32_e32 v109, 0xbfb8aa3b, v86
	v_exp_f32_e32 v109, v109
	s_nop 0
	v_add_f32_e32 v110, 1.0, v109
	v_div_scale_f32 v104, s[96:97], v110, v110, v86
	v_rcp_f32_e32 v105, v104
	v_div_scale_f32 v106, vcc, v86, v110, v86
	v_fma_f32 v107, -v104, v105, 1.0
	v_fmac_f32_e32 v105, v107, v105
	v_mul_f32_e32 v107, v106, v105
	v_fma_f32 v108, -v104, v107, v106
	v_fmac_f32_e32 v107, v108, v105
	v_fma_f32 v106, -v104, v107, v106
	v_div_fmas_f32 v106, v106, v105, v107
	v_div_fixup_f32 v102, v106, v110, v86
	v_mul_f32_e32 v109, 0xbfb8aa3b, v83
	v_exp_f32_e32 v109, v109
	s_nop 0
	v_add_f32_e32 v110, 1.0, v109
	v_div_scale_f32 v104, s[96:97], v110, v110, v83
; DI unsigned pack2(float a, float b) { return (unsigned)f2bf(a) | ((unsigned)f2bf(b) << 16); }
; DI float bflo(unsigned d) { return __uint_as_float(d << 16); }
; DI float bfhi(unsigned d) { return __uint_as_float(d & 0xffff0000u); }
; DI float siluf(float x) { return x / (1.f + __expf(-x)); }
; DI void phase4(const Params& p) {
;     ...
;       float ss = wave_sum(o0 * o0 + o1 * o1);
;       float rs = rsqrtf(ss * (1.f / 128.f) + EPS);
;       float2 gn = *(const float2*)&p.g_onorm[lane * 2];
;       float y0 = o0 * rs * gn.x * siluf(bflo(zv)), y1 = o1 * rs * gn.y * siluf(bfhi(zv));
;       *(unsigned*)&dst[h * 128 + lane * 2] = pack2(y0, y1);
;     }
;     {
;       const int h = lane >> 4;
;       float l0 = p.lse[((size_t)0 * MT + row) * 4 + h], l1 = p.lse[((size_t)1 * MT + row) * 4 + h], l2 = p.lse[((size_t)2 * MT + row) * 4 + h];
;       float m = fmaxf(l0, fmaxf(l1, l2));
;       float e0 = __expf(l0 - m), e1 = __expf(l1 - m), e2 = __expf(l2 - m);
;       float inv = 1.f / (e0 + e1 + e2);
;       uint2 a = *(const uint2*)&p.osw[((size_t)0 * MT + row) * 256 + lane * 4];
;       uint2 c = *(const uint2*)&p.osw[((size_t)1 * MT + row) * 256 + lane * 4];
;       uint2 d = *(const uint2*)&p.osw[((size_t)2 * MT + row) * 256 + lane * 4];
;       e0 *= inv; e1 *= inv; e2 *= inv;
;       float y0 = e0 * bflo(a.x) + e1 * bflo(c.x) + e2 * bflo(d.x);
;       float y1 = e0 * bfhi(a.x) + e1 * bfhi(c.x) + e2 * bfhi(d.x);
;       float y2 = e0 * bflo(a.y) + e1 * bflo(c.y) + e2 * bflo(d.y);
;       float y3 = e0 * bfhi(a.y) + e1 * bfhi(c.y) + e2 * bfhi(d.y);
;       *(uint2*)&dst[512 + lane * 4] = make_uint2(pack2(y0, y1), pack2(y2, y3));
;     }
	v_rcp_f32_e32 v105, v104
	v_div_scale_f32 v106, vcc, v83, v110, v83
	v_fma_f32 v107, -v104, v105, 1.0
	v_fmac_f32_e32 v105, v107, v105
	v_mul_f32_e32 v107, v106, v105
	v_fma_f32 v108, -v104, v107, v106
	v_fmac_f32_e32 v107, v108, v105
	v_fma_f32 v106, -v104, v107, v106
	v_div_fmas_f32 v106, v106, v105, v107
	v_div_fixup_f32 v99, v106, v110, v83
	v_mul_f32_e32 v109, 0xbfb8aa3b, v87
	v_exp_f32_e32 v109, v109
	s_nop 0
	v_add_f32_e32 v110, 1.0, v109
	v_div_scale_f32 v104, s[96:97], v110, v110, v87
	v_rcp_f32_e32 v105, v104
	v_div_scale_f32 v106, vcc, v87, v110, v87
	v_fma_f32 v107, -v104, v105, 1.0
	v_fmac_f32_e32 v105, v107, v105
	v_mul_f32_e32 v107, v106, v105
	v_fma_f32 v108, -v104, v107, v106
	v_fmac_f32_e32 v107, v108, v105
	v_fma_f32 v106, -v104, v107, v106
	v_div_fmas_f32 v106, v106, v105, v107
	v_div_fixup_f32 v103, v106, v110, v87
	v_fmamk_f32 v88, v88, 0x3c000000, v9
	v_mul_f32_e32 v92, 0x4b800000, v88
	v_cmp_gt_f32_e32 vcc, 0x800000, v88
	s_nop 1
	v_cndmask_b32_e32 v88, v88, v92, vcc
	v_rsq_f32_e32 v88, v88
	s_nop 0
	v_mul_f32_e32 v92, 0x45800000, v88
	v_cndmask_b32_e32 v88, v88, v92, vcc
	v_mul_f32_e32 v72, v88, v72
	v_mul_f32_e32 v76, v88, v76
	v_mul_f32_e32 v72, v18, v72
	v_mul_f32_e32 v76, v19, v76
	v_mul_f32_e32 v72, v96, v72
	v_mul_f32_e32 v76, v100, v76
	v_bfe_u32 v92, v72, 16, 1
	v_add3_u32 v72, v72, v92, s23
	v_bfe_u32 v92, v76, 16, 1
	v_add3_u32 v76, v76, v92, s23
	v_lshrrev_b32_e32 v72, 16, v72
	v_and_or_b32 v72, v76, s1, v72
	v_fmamk_f32 v89, v89, 0x3c000000, v9
	v_mul_f32_e32 v93, 0x4b800000, v89
	v_cmp_gt_f32_e32 vcc, 0x800000, v89
	s_nop 1
	v_cndmask_b32_e32 v89, v89, v93, vcc
	v_rsq_f32_e32 v89, v89
	s_nop 0
	v_mul_f32_e32 v93, 0x45800000, v89
	v_cndmask_b32_e32 v89, v89, v93, vcc
	v_mul_f32_e32 v73, v89, v73
	v_mul_f32_e32 v77, v89, v77
	v_mul_f32_e32 v73, v18, v73
	v_mul_f32_e32 v77, v19, v77
	v_mul_f32_e32 v73, v97, v73
	v_mul_f32_e32 v77, v101, v77
	v_bfe_u32 v93, v73, 16, 1
	v_add3_u32 v73, v73, v93, s23
	v_bfe_u32 v93, v77, 16, 1
	v_add3_u32 v77, v77, v93, s23
	v_lshrrev_b32_e32 v73, 16, v73
	v_and_or_b32 v73, v77, s1, v73
	v_fmamk_f32 v90, v90, 0x3c000000, v9
	v_mul_f32_e32 v94, 0x4b800000, v90
	v_cmp_gt_f32_e32 vcc, 0x800000, v90
	s_nop 1
	v_cndmask_b32_e32 v90, v90, v94, vcc
	v_rsq_f32_e32 v90, v90
	s_nop 0
	v_mul_f32_e32 v94, 0x45800000, v90
	v_cndmask_b32_e32 v90, v90, v94, vcc
	v_mul_f32_e32 v74, v90, v74
	v_mul_f32_e32 v78, v90, v78
	v_mul_f32_e32 v74, v18, v74
	v_mul_f32_e32 v78, v19, v78
	v_mul_f32_e32 v74, v98, v74
	v_mul_f32_e32 v78, v102, v78
	v_bfe_u32 v94, v74, 16, 1
	v_add3_u32 v74, v74, v94, s23
	v_bfe_u32 v94, v78, 16, 1
	v_add3_u32 v78, v78, v94, s23
	v_lshrrev_b32_e32 v74, 16, v74
	v_and_or_b32 v74, v78, s1, v74
	v_fmamk_f32 v91, v91, 0x3c000000, v9
	v_mul_f32_e32 v95, 0x4b800000, v91
	v_cmp_gt_f32_e32 vcc, 0x800000, v91
	s_nop 1
	v_cndmask_b32_e32 v91, v91, v95, vcc
	v_rsq_f32_e32 v91, v91
	s_nop 0
	v_mul_f32_e32 v95, 0x45800000, v91
	v_cndmask_b32_e32 v91, v91, v95, vcc
	v_mul_f32_e32 v75, v91, v75
	v_mul_f32_e32 v79, v91, v79
	v_mul_f32_e32 v75, v18, v75
	v_mul_f32_e32 v79, v19, v79
	v_mul_f32_e32 v75, v99, v75
	v_mul_f32_e32 v79, v103, v79
	v_bfe_u32 v95, v75, 16, 1
	v_add3_u32 v75, v75, v95, s23
	v_bfe_u32 v95, v79, 16, 1
	v_add3_u32 v79, v79, v95, s23
	v_lshrrev_b32_e32 v75, 16, v75
	v_and_or_b32 v75, v79, s1, v75
	v_max3_f32 v112, v40, v41, v42
	v_sub_f32_e32 v113, v40, v112
	v_mul_f32_e32 v113, 0x3fb8aa3b, v113
	v_sub_f32_e32 v114, v41, v112
	v_mul_f32_e32 v114, 0x3fb8aa3b, v114
	v_sub_f32_e32 v115, v42, v112
	v_mul_f32_e32 v115, 0x3fb8aa3b, v115
	v_exp_f32_e32 v113, v113
	v_exp_f32_e32 v114, v114
	v_exp_f32_e32 v115, v115
	s_nop 0
	v_add_f32_e32 v116, v113, v114
	v_add_f32_e32 v116, v115, v116
	v_mov_b32_e32 v117, 1.0
	v_div_scale_f32 v104, s[96:97], v116, v116, v117
	v_rcp_f32_e32 v105, v104
	v_div_scale_f32 v106, vcc, v117, v116, v117
	v_fma_f32 v107, -v104, v105, 1.0
	v_fmac_f32_e32 v105, v107, v105
	v_mul_f32_e32 v107, v106, v105
	v_fma_f32 v108, -v104, v107, v106
	v_fmac_f32_e32 v107, v108, v105
	v_fma_f32 v106, -v104, v107, v106
	v_div_fmas_f32 v106, v106, v105, v107
	v_div_fixup_f32 v118, v106, v116, v117
	v_mul_f32_e32 v113, v113, v118
	v_mul_f32_e32 v114, v114, v118
	v_mul_f32_e32 v115, v115, v118
	v_lshlrev_b32_e32 v124, 16, v44
	v_and_b32_e32 v125, 0xffff0000, v44
	v_lshlrev_b32_e32 v126, 16, v45
	v_and_b32_e32 v127, 0xffff0000, v45
	v_mul_f32_e32 v120, v113, v124
	v_mul_f32_e32 v121, v113, v125
	v_mul_f32_e32 v122, v113, v126
	v_mul_f32_e32 v123, v113, v127
	v_lshlrev_b32_e32 v124, 16, v46
	v_and_b32_e32 v125, 0xffff0000, v46
	v_lshlrev_b32_e32 v126, 16, v47
	v_and_b32_e32 v127, 0xffff0000, v47
	v_fmac_f32_e32 v120, v114, v124
	v_fmac_f32_e32 v121, v114, v125
	v_fmac_f32_e32 v122, v114, v126
	v_fmac_f32_e32 v123, v114, v127
	v_lshlrev_b32_e32 v124, 16, v48
	v_and_b32_e32 v125, 0xffff0000, v48
	v_lshlrev_b32_e32 v126, 16, v49
	v_and_b32_e32 v127, 0xffff0000, v49
	v_fmac_f32_e32 v120, v115, v124
	v_fmac_f32_e32 v121, v115, v125
	v_fmac_f32_e32 v122, v115, v126
	v_fmac_f32_e32 v123, v115, v127
	v_bfe_u32 v124, v120, 16, 1
	v_add3_u32 v120, v120, v124, s23
	v_bfe_u32 v125, v121, 16, 1
	v_add3_u32 v121, v121, v125, s23
	v_bfe_u32 v126, v122, 16, 1
	v_add3_u32 v122, v122, v126, s23
	v_bfe_u32 v127, v123, 16, 1
	v_add3_u32 v123, v123, v127, s23
	v_lshrrev_b32_e32 v120, 16, v120
	v_and_or_b32 v120, v121, s1, v120
	v_lshrrev_b32_e32 v122, 16, v122
	v_and_or_b32 v121, v123, s1, v122
	s_mul_i32 s0, s10, 0x600
	s_add_u32 s88, s14, s0
	s_addc_u32 s89, s15, 0
	global_store_dword v1, v72, s[88:89] offset:0
	global_store_dword v1, v73, s[88:89] offset:256
	global_store_dword v1, v74, s[88:89] offset:512
	global_store_dword v1, v75, s[88:89] offset:768
	global_store_dwordx2 v2, v[120:121], s[88:89] offset:1024
	s_mov_b32 s10, s22
	s_cmp_lt_i32 s10, 0x8080
	s_cbranch_scc0 .Lp4_done
	s_add_i32 s22, s10, s78
	s_cmp_lt_i32 s22, 0x8080
	s_cbranch_scc0 .Lp4_lastB
	s_lshl_b32 s0, s22, 10
	s_add_u32 s92, s12, s0
	s_addc_u32 s93, s13, 0
	s_mul_i32 s0, s22, 0x2200
	s_add_u32 s0, s0, 0xc00
	s_add_u32 s94, s20, s0
	s_addc_u32 s95, s21, 0
	s_lshl_b32 s0, s22, 4
	s_add_u32 s96, s18, s0
	s_addc_u32 s97, s19, 0
	s_lshl_b32 s0, s22, 9
	s_add_u32 s90, s16, s0
	s_addc_u32 s91, s17, 0
	global_load_dword v32, v1, s[92:93] offset:0
	global_load_dword v33, v1, s[92:93] offset:256
	global_load_dword v34, v1, s[92:93] offset:512
	global_load_dword v35, v1, s[92:93] offset:768
	global_load_dword v36, v1, s[94:95] offset:0
	global_load_dword v37, v1, s[94:95] offset:256
	global_load_dword v38, v1, s[94:95] offset:512
	global_load_dword v39, v1, s[94:95] offset:768
	global_load_dword v40, v3, s[96:97]
	global_load_dword v41, v4, s[96:97]
	global_load_dword v42, v5, s[96:97]
	global_load_dwordx2 v[44:45], v6, s[90:91]
	global_load_dwordx2 v[46:47], v7, s[90:91]
	global_load_dwordx2 v[48:49], v8, s[90:91]
	s_waitcnt vmcnt(19)
	s_branch .Lp4_goB

; DI float bflo(unsigned d) { return __uint_as_float(d << 16); }
; DI float bfhi(unsigned d) { return __uint_as_float(d & 0xffff0000u); }
; DI float siluf(float x) { return x / (1.f + __expf(-x)); }
; DI void phase4(const Params& p) {
;     ...
;     for (int h = 0; h < 4; ++h) {
;       unsigned ov = *(const unsigned*)&p.odn[(size_t)row * 512 + h * 128 + lane * 2];
;       unsigned zv = *(const unsigned*)&p.proj[(size_t)row * NP + 1536 + h * 128 + lane * 2];
;       float o0 = bflo(ov), o1 = bfhi(ov);
;       float ss = wave_sum(o0 * o0 + o1 * o1);
;       float rs = rsqrtf(ss * (1.f / 128.f) + EPS);
;       float2 gn = *(const float2*)&p.g_onorm[lane * 2];
;       float y0 = o0 * rs * gn.x * siluf(bflo(zv)), y1 = o1 * rs * gn.y * siluf(bfhi(zv));
.Lp4_goB:
	v_lshlrev_b32_e32 v72, 16, v52
	v_and_b32_e32 v76, 0xffff0000, v52
	v_lshlrev_b32_e32 v80, 16, v56
	v_and_b32_e32 v84, 0xffff0000, v56
	v_mul_f32_e32 v88, v72, v72
	v_mul_f32_e32 v92, v76, v76
	v_add_f32_e32 v88, v88, v92
	v_lshlrev_b32_e32 v73, 16, v53
	v_and_b32_e32 v77, 0xffff0000, v53
	v_lshlrev_b32_e32 v81, 16, v57
	v_and_b32_e32 v85, 0xffff0000, v57
	v_mul_f32_e32 v89, v73, v73
	v_mul_f32_e32 v93, v77, v77
	v_add_f32_e32 v89, v89, v93
	v_lshlrev_b32_e32 v74, 16, v54
	v_and_b32_e32 v78, 0xffff0000, v54
	v_lshlrev_b32_e32 v82, 16, v58
	v_and_b32_e32 v86, 0xffff0000, v58
	v_mul_f32_e32 v90, v74, v74
	v_mul_f32_e32 v94, v78, v78
	v_add_f32_e32 v90, v90, v94
	v_lshlrev_b32_e32 v75, 16, v55
	v_and_b32_e32 v79, 0xffff0000, v55
	v_lshlrev_b32_e32 v83, 16, v59
	v_and_b32_e32 v87, 0xffff0000, v59
	v_mul_f32_e32 v91, v75, v75
	v_mul_f32_e32 v95, v79, v79
	v_add_f32_e32 v91, v91, v95
	ds_bpermute_b32 v92, v12, v88
	ds_bpermute_b32 v93, v12, v89
	ds_bpermute_b32 v94, v12, v90
	ds_bpermute_b32 v95, v12, v91
	s_waitcnt lgkmcnt(0)
	v_add_f32_e32 v88, v88, v92
	v_add_f32_e32 v89, v89, v93
	v_add_f32_e32 v90, v90, v94
	v_add_f32_e32 v91, v91, v95
	ds_bpermute_b32 v92, v13, v88
	ds_bpermute_b32 v93, v13, v89
	ds_bpermute_b32 v94, v13, v90
	ds_bpermute_b32 v95, v13, v91
	s_waitcnt lgkmcnt(0)
	v_add_f32_e32 v88, v88, v92
	v_add_f32_e32 v89, v89, v93
	v_add_f32_e32 v90, v90, v94
	v_add_f32_e32 v91, v91, v95
	ds_bpermute_b32 v92, v14, v88
	ds_bpermute_b32 v93, v14, v89
	ds_bpermute_b32 v94, v14, v90
	ds_bpermute_b32 v95, v14, v91
	s_waitcnt lgkmcnt(0)
	v_add_f32_e32 v88, v88, v92
	v_add_f32_e32 v89, v89, v93
	v_add_f32_e32 v90, v90, v94
	v_add_f32_e32 v91, v91, v95
	ds_bpermute_b32 v92, v15, v88
	ds_bpermute_b32 v93, v15, v89
	ds_bpermute_b32 v94, v15, v90
	ds_bpermute_b32 v95, v15, v91
	s_waitcnt lgkmcnt(0)
	v_add_f32_e32 v88, v88, v92
	v_add_f32_e32 v89, v89, v93
	v_add_f32_e32 v90, v90, v94
	v_add_f32_e32 v91, v91, v95
	ds_bpermute_b32 v92, v16, v88
	ds_bpermute_b32 v93, v16, v89
	ds_bpermute_b32 v94, v16, v90
	ds_bpermute_b32 v95, v16, v91
	s_waitcnt lgkmcnt(0)
	v_add_f32_e32 v88, v88, v92
	v_add_f32_e32 v89, v89, v93
	v_add_f32_e32 v90, v90, v94
	v_add_f32_e32 v91, v91, v95
	ds_bpermute_b32 v92, v17, v88
	ds_bpermute_b32 v93, v17, v89
	ds_bpermute_b32 v94, v17, v90
	ds_bpermute_b32 v95, v17, v91
	s_waitcnt lgkmcnt(0)
	v_add_f32_e32 v88, v88, v92
	v_add_f32_e32 v89, v89, v93
	v_add_f32_e32 v90, v90, v94
	v_add_f32_e32 v91, v91, v95
	v_mul_f32_e32 v109, 0xbfb8aa3b, v80
	v_exp_f32_e32 v109, v109
	s_nop 0
	v_add_f32_e32 v110, 1.0, v109
	v_div_scale_f32 v104, s[96:97], v110, v110, v80
	v_rcp_f32_e32 v105, v104
	v_div_scale_f32 v106, vcc, v80, v110, v80
	v_fma_f32 v107, -v104, v105, 1.0
	v_fmac_f32_e32 v105, v107, v105
	v_mul_f32_e32 v107, v106, v105
	v_fma_f32 v108, -v104, v107, v106
	v_fmac_f32_e32 v107, v108, v105
	v_fma_f32 v106, -v104, v107, v106
	v_div_fmas_f32 v106, v106, v105, v107
	v_div_fixup_f32 v96, v106, v110, v80
	v_mul_f32_e32 v109, 0xbfb8aa3b, v84
	v_exp_f32_e32 v109, v109
	s_nop 0
	v_add_f32_e32 v110, 1.0, v109
	v_div_scale_f32 v104, s[96:97], v110, v110, v84
	v_rcp_f32_e32 v105, v104
	v_div_scale_f32 v106, vcc, v84, v110, v84
	v_fma_f32 v107, -v104, v105, 1.0
	v_fmac_f32_e32 v105, v107, v105
	v_mul_f32_e32 v107, v106, v105
	v_fma_f32 v108, -v104, v107, v106
	v_fmac_f32_e32 v107, v108, v105
	v_fma_f32 v106, -v104, v107, v106
	v_div_fmas_f32 v106, v106, v105, v107
	v_div_fixup_f32 v100, v106, v110, v84
	v_mul_f32_e32 v109, 0xbfb8aa3b, v81
	v_exp_f32_e32 v109, v109
	s_nop 0
	v_add_f32_e32 v110, 1.0, v109
	v_div_scale_f32 v104, s[96:97], v110, v110, v81
	v_rcp_f32_e32 v105, v104
	v_div_scale_f32 v106, vcc, v81, v110, v81
	v_fma_f32 v107, -v104, v105, 1.0
	v_fmac_f32_e32 v105, v107, v105
	v_mul_f32_e32 v107, v106, v105
	v_fma_f32 v108, -v104, v107, v106
	v_fmac_f32_e32 v107, v108, v105
	v_fma_f32 v106, -v104, v107, v106
	v_div_fmas_f32 v106, v106, v105, v107
	v_div_fixup_f32 v97, v106, v110, v81
	v_mul_f32_e32 v109, 0xbfb8aa3b, v85
	v_exp_f32_e32 v109, v109
	s_nop 0
	v_add_f32_e32 v110, 1.0, v109
	v_div_scale_f32 v104, s[96:97], v110, v110, v85
	v_rcp_f32_e32 v105, v104
	v_div_scale_f32 v106, vcc, v85, v110, v85
	v_fma_f32 v107, -v104, v105, 1.0
	v_fmac_f32_e32 v105, v107, v105
	v_mul_f32_e32 v107, v106, v105
	v_fma_f32 v108, -v104, v107, v106
	v_fmac_f32_e32 v107, v108, v105
	v_fma_f32 v106, -v104, v107, v106
	v_div_fmas_f32 v106, v106, v105, v107
	v_div_fixup_f32 v101, v106, v110, v85
	v_mul_f32_e32 v109, 0xbfb8aa3b, v82
	v_exp_f32_e32 v109, v109
	s_nop 0
	v_add_f32_e32 v110, 1.0, v109
	v_div_scale_f32 v104, s[96:97], v110, v110, v82
	v_rcp_f32_e32 v105, v104
	v_div_scale_f32 v106, vcc, v82, v110, v82
	v_fma_f32 v107, -v104, v105, 1.0
	v_fmac_f32_e32 v105, v107, v105
	v_mul_f32_e32 v107, v106, v105
	v_fma_f32 v108, -v104, v107, v106
	v_fmac_f32_e32 v107, v108, v105
	v_fma_f32 v106, -v104, v107, v106
	v_div_fmas_f32 v106, v106, v105, v107
	v_div_fixup_f32 v98, v106, v110, v82
	v_mul_f32_e32 v109, 0xbfb8aa3b, v86
	v_exp_f32_e32 v109, v109
	s_nop 0
	v_add_f32_e32 v110, 1.0, v109
	v_div_scale_f32 v104, s[96:97], v110, v110, v86
	v_rcp_f32_e32 v105, v104
	v_div_scale_f32 v106, vcc, v86, v110, v86
	v_fma_f32 v107, -v104, v105, 1.0
	v_fmac_f32_e32 v105, v107, v105
	v_mul_f32_e32 v107, v106, v105
	v_fma_f32 v108, -v104, v107, v106
	v_fmac_f32_e32 v107, v108, v105
	v_fma_f32 v106, -v104, v107, v106
	v_div_fmas_f32 v106, v106, v105, v107
	v_div_fixup_f32 v102, v106, v110, v86
	v_mul_f32_e32 v109, 0xbfb8aa3b, v83
	v_exp_f32_e32 v109, v109
	s_nop 0
	v_add_f32_e32 v110, 1.0, v109
	v_div_scale_f32 v104, s[96:97], v110, v110, v83
; DI unsigned pack2(float a, float b) { return (unsigned)f2bf(a) | ((unsigned)f2bf(b) << 16); }
; DI float bflo(unsigned d) { return __uint_as_float(d << 16); }
; DI float bfhi(unsigned d) { return __uint_as_float(d & 0xffff0000u); }
; DI float siluf(float x) { return x / (1.f + __expf(-x)); }
; DI unsigned xb_add(unsigned* q, unsigned v) { return __hip_atomic_fetch_add(q, v, __ATOMIC_RELAXED, __HIP_MEMORY_SCOPE_AGENT); }
; DI void phase4(const Params& p) {
;     ...
;       float ss = wave_sum(o0 * o0 + o1 * o1);
;       float rs = rsqrtf(ss * (1.f / 128.f) + EPS);
;       float2 gn = *(const float2*)&p.g_onorm[lane * 2];
;       float y0 = o0 * rs * gn.x * siluf(bflo(zv)), y1 = o1 * rs * gn.y * siluf(bfhi(zv));
;       *(unsigned*)&dst[h * 128 + lane * 2] = pack2(y0, y1);
;     }
;     {
;       const int h = lane >> 4;
;       float l0 = p.lse[((size_t)0 * MT + row) * 4 + h], l1 = p.lse[((size_t)1 * MT + row) * 4 + h], l2 = p.lse[((size_t)2 * MT + row) * 4 + h];
;       float m = fmaxf(l0, fmaxf(l1, l2));
;       float e0 = __expf(l0 - m), e1 = __expf(l1 - m), e2 = __expf(l2 - m);
;       float inv = 1.f / (e0 + e1 + e2);
;       uint2 a = *(const uint2*)&p.osw[((size_t)0 * MT + row) * 256 + lane * 4];
;       uint2 c = *(const uint2*)&p.osw[((size_t)1 * MT + row) * 256 + lane * 4];
;       uint2 d = *(const uint2*)&p.osw[((size_t)2 * MT + row) * 256 + lane * 4];
;       e0 *= inv; e1 *= inv; e2 *= inv;
;       float y0 = e0 * bflo(a.x) + e1 * bflo(c.x) + e2 * bflo(d.x);
;       float y1 = e0 * bfhi(a.x) + e1 * bfhi(c.x) + e2 * bfhi(d.x);
;       float y2 = e0 * bflo(a.y) + e1 * bflo(c.y) + e2 * bflo(d.y);
;       float y3 = e0 * bfhi(a.y) + e1 * bfhi(c.y) + e2 * bfhi(d.y);
;       *(uint2*)&dst[512 + lane * 4] = make_uint2(pack2(y0, y1), pack2(y2, y3));
;     }
; DI void xcd_barrier(const XcdBarrier& b) {
;   asm volatile("s_waitcnt vmcnt(0)" ::: "memory");
;   __syncthreads();
;   if (threadIdx.x == 0) {
;     unsigned* bar = b.bar;
;     __builtin_amdgcn_s_waitcnt(0);
;     unsigned nloc = b.st[0], nx = b.st[1];
;     if (nloc == 0u) { xcd_barrier_complete(bar, b.x, nloc, nx); b.st[0] = nloc; b.st[1] = nx; }
;     const unsigned old = xb_add(&bar[XB_XSUB(b.x)], 1u);
;     const unsigned gen = old / nloc;
	v_rcp_f32_e32 v105, v104
	v_div_scale_f32 v106, vcc, v83, v110, v83
	v_fma_f32 v107, -v104, v105, 1.0
	v_fmac_f32_e32 v105, v107, v105
	v_mul_f32_e32 v107, v106, v105
	v_fma_f32 v108, -v104, v107, v106
	v_fmac_f32_e32 v107, v108, v105
	v_fma_f32 v106, -v104, v107, v106
	v_div_fmas_f32 v106, v106, v105, v107
	v_div_fixup_f32 v99, v106, v110, v83
	v_mul_f32_e32 v109, 0xbfb8aa3b, v87
	v_exp_f32_e32 v109, v109
	s_nop 0
	v_add_f32_e32 v110, 1.0, v109
	v_div_scale_f32 v104, s[96:97], v110, v110, v87
	v_rcp_f32_e32 v105, v104
	v_div_scale_f32 v106, vcc, v87, v110, v87
	v_fma_f32 v107, -v104, v105, 1.0
	v_fmac_f32_e32 v105, v107, v105
	v_mul_f32_e32 v107, v106, v105
	v_fma_f32 v108, -v104, v107, v106
	v_fmac_f32_e32 v107, v108, v105
	v_fma_f32 v106, -v104, v107, v106
	v_div_fmas_f32 v106, v106, v105, v107
	v_div_fixup_f32 v103, v106, v110, v87
	v_fmamk_f32 v88, v88, 0x3c000000, v9
	v_mul_f32_e32 v92, 0x4b800000, v88
	v_cmp_gt_f32_e32 vcc, 0x800000, v88
	s_nop 1
	v_cndmask_b32_e32 v88, v88, v92, vcc
	v_rsq_f32_e32 v88, v88
	s_nop 0
	v_mul_f32_e32 v92, 0x45800000, v88
	v_cndmask_b32_e32 v88, v88, v92, vcc
	v_mul_f32_e32 v72, v88, v72
	v_mul_f32_e32 v76, v88, v76
	v_mul_f32_e32 v72, v18, v72
	v_mul_f32_e32 v76, v19, v76
	v_mul_f32_e32 v72, v96, v72
	v_mul_f32_e32 v76, v100, v76
	v_bfe_u32 v92, v72, 16, 1
	v_add3_u32 v72, v72, v92, s23
	v_bfe_u32 v92, v76, 16, 1
	v_add3_u32 v76, v76, v92, s23
	v_lshrrev_b32_e32 v72, 16, v72
	v_and_or_b32 v72, v76, s1, v72
	v_fmamk_f32 v89, v89, 0x3c000000, v9
	v_mul_f32_e32 v93, 0x4b800000, v89
	v_cmp_gt_f32_e32 vcc, 0x800000, v89
	s_nop 1
	v_cndmask_b32_e32 v89, v89, v93, vcc
	v_rsq_f32_e32 v89, v89
	s_nop 0
	v_mul_f32_e32 v93, 0x45800000, v89
	v_cndmask_b32_e32 v89, v89, v93, vcc
	v_mul_f32_e32 v73, v89, v73
	v_mul_f32_e32 v77, v89, v77
	v_mul_f32_e32 v73, v18, v73
	v_mul_f32_e32 v77, v19, v77
	v_mul_f32_e32 v73, v97, v73
	v_mul_f32_e32 v77, v101, v77
	v_bfe_u32 v93, v73, 16, 1
	v_add3_u32 v73, v73, v93, s23
	v_bfe_u32 v93, v77, 16, 1
	v_add3_u32 v77, v77, v93, s23
	v_lshrrev_b32_e32 v73, 16, v73
	v_and_or_b32 v73, v77, s1, v73
	v_fmamk_f32 v90, v90, 0x3c000000, v9
	v_mul_f32_e32 v94, 0x4b800000, v90
	v_cmp_gt_f32_e32 vcc, 0x800000, v90
	s_nop 1
	v_cndmask_b32_e32 v90, v90, v94, vcc
	v_rsq_f32_e32 v90, v90
	s_nop 0
	v_mul_f32_e32 v94, 0x45800000, v90
	v_cndmask_b32_e32 v90, v90, v94, vcc
	v_mul_f32_e32 v74, v90, v74
	v_mul_f32_e32 v78, v90, v78
	v_mul_f32_e32 v74, v18, v74
	v_mul_f32_e32 v78, v19, v78
	v_mul_f32_e32 v74, v98, v74
	v_mul_f32_e32 v78, v102, v78
	v_bfe_u32 v94, v74, 16, 1
	v_add3_u32 v74, v74, v94, s23
	v_bfe_u32 v94, v78, 16, 1
	v_add3_u32 v78, v78, v94, s23
	v_lshrrev_b32_e32 v74, 16, v74
	v_and_or_b32 v74, v78, s1, v74
	v_fmamk_f32 v91, v91, 0x3c000000, v9
	v_mul_f32_e32 v95, 0x4b800000, v91
	v_cmp_gt_f32_e32 vcc, 0x800000, v91
	s_nop 1
	v_cndmask_b32_e32 v91, v91, v95, vcc
	v_rsq_f32_e32 v91, v91
	s_nop 0
	v_mul_f32_e32 v95, 0x45800000, v91
	v_cndmask_b32_e32 v91, v91, v95, vcc
	v_mul_f32_e32 v75, v91, v75
	v_mul_f32_e32 v79, v91, v79
	v_mul_f32_e32 v75, v18, v75
	v_mul_f32_e32 v79, v19, v79
	v_mul_f32_e32 v75, v99, v75
	v_mul_f32_e32 v79, v103, v79
	v_bfe_u32 v95, v75, 16, 1
	v_add3_u32 v75, v75, v95, s23
	v_bfe_u32 v95, v79, 16, 1
	v_add3_u32 v79, v79, v95, s23
	v_lshrrev_b32_e32 v75, 16, v75
	v_and_or_b32 v75, v79, s1, v75
	v_max3_f32 v112, v60, v61, v62
	v_sub_f32_e32 v113, v60, v112
	v_mul_f32_e32 v113, 0x3fb8aa3b, v113
	v_sub_f32_e32 v114, v61, v112
	v_mul_f32_e32 v114, 0x3fb8aa3b, v114
	v_sub_f32_e32 v115, v62, v112
	v_mul_f32_e32 v115, 0x3fb8aa3b, v115
	v_exp_f32_e32 v113, v113
	v_exp_f32_e32 v114, v114
	v_exp_f32_e32 v115, v115
	s_nop 0
	v_add_f32_e32 v116, v113, v114
	v_add_f32_e32 v116, v115, v116
	v_mov_b32_e32 v117, 1.0
	v_div_scale_f32 v104, s[96:97], v116, v116, v117
	v_rcp_f32_e32 v105, v104
	v_div_scale_f32 v106, vcc, v117, v116, v117
	v_fma_f32 v107, -v104, v105, 1.0
	v_fmac_f32_e32 v105, v107, v105
	v_mul_f32_e32 v107, v106, v105
	v_fma_f32 v108, -v104, v107, v106
	v_fmac_f32_e32 v107, v108, v105
	v_fma_f32 v106, -v104, v107, v106
	v_div_fmas_f32 v106, v106, v105, v107
	v_div_fixup_f32 v118, v106, v116, v117
	v_mul_f32_e32 v113, v113, v118
	v_mul_f32_e32 v114, v114, v118
	v_mul_f32_e32 v115, v115, v118
	v_lshlrev_b32_e32 v124, 16, v64
	v_and_b32_e32 v125, 0xffff0000, v64
	v_lshlrev_b32_e32 v126, 16, v65
	v_and_b32_e32 v127, 0xffff0000, v65
	v_mul_f32_e32 v120, v113, v124
	v_mul_f32_e32 v121, v113, v125
	v_mul_f32_e32 v122, v113, v126
	v_mul_f32_e32 v123, v113, v127
	v_lshlrev_b32_e32 v124, 16, v66
	v_and_b32_e32 v125, 0xffff0000, v66
	v_lshlrev_b32_e32 v126, 16, v67
	v_and_b32_e32 v127, 0xffff0000, v67
	v_fmac_f32_e32 v120, v114, v124
	v_fmac_f32_e32 v121, v114, v125
	v_fmac_f32_e32 v122, v114, v126
	v_fmac_f32_e32 v123, v114, v127
	v_lshlrev_b32_e32 v124, 16, v68
	v_and_b32_e32 v125, 0xffff0000, v68
	v_lshlrev_b32_e32 v126, 16, v69
	v_and_b32_e32 v127, 0xffff0000, v69
	v_fmac_f32_e32 v120, v115, v124
	v_fmac_f32_e32 v121, v115, v125
	v_fmac_f32_e32 v122, v115, v126
	v_fmac_f32_e32 v123, v115, v127
	v_bfe_u32 v124, v120, 16, 1
	v_add3_u32 v120, v120, v124, s23
	v_bfe_u32 v125, v121, 16, 1
	v_add3_u32 v121, v121, v125, s23
	v_bfe_u32 v126, v122, 16, 1
	v_add3_u32 v122, v122, v126, s23
	v_bfe_u32 v127, v123, 16, 1
	v_add3_u32 v123, v123, v127, s23
	v_lshrrev_b32_e32 v120, 16, v120
	v_and_or_b32 v120, v121, s1, v120
	v_lshrrev_b32_e32 v122, 16, v122
	v_and_or_b32 v121, v123, s1, v122
	s_mul_i32 s0, s10, 0x600
	s_add_u32 s88, s14, s0
	s_addc_u32 s89, s15, 0
	global_store_dword v1, v72, s[88:89] offset:0
	global_store_dword v1, v73, s[88:89] offset:256
	global_store_dword v1, v74, s[88:89] offset:512
	global_store_dword v1, v75, s[88:89] offset:768
	global_store_dwordx2 v2, v[120:121], s[88:89] offset:1024
	s_mov_b32 s10, s22
	s_cmp_lt_i32 s10, 0x8080
	s_cbranch_scc1 .Lp4_loop
.Lp4_done:
.LBB0_672:
	s_or_b64 exec, exec, s[2:3]
	s_waitcnt vmcnt(0)
	v_readlane_b32 s2, v255, 0
	v_readlane_b32 s3, v255, 1
	s_waitcnt lgkmcnt(0)
	s_barrier
	s_and_saveexec_b64 s[0:1], s[2:3]
	s_xor_b64 s[2:3], exec, s[0:1]
	s_cbranch_execz .LBB0_717
	v_mov_b32_e32 v0, 0x10200
	s_waitcnt vmcnt(0) expcnt(0) lgkmcnt(0)
	ds_read_b32 v2, v0
	v_mov_b32_e32 v0, 0x10204
	ds_read_b32 v4, v0
	s_waitcnt lgkmcnt(1)
	v_cmp_ne_u32_e32 vcc, 0, v2
	s_cbranch_vccnz .LBB0_687
	v_readlane_b32 s0, v255, 2
	s_mul_i32 s26, s85, s0
	s_mov_b64 s[0:1], 0x1000
	v_lshl_add_u64 v[0:1], v[132:133], 0, s[0:1]
	s_mov_b64 s[0:1], 0x1100
	v_lshl_add_u64 v[2:3], v[132:133], 0, s[0:1]
	s_mov_b64 s[0:1], 0x1200
	s_waitcnt lgkmcnt(0)
	v_lshl_add_u64 v[4:5], v[132:133], 0, s[0:1]
	s_mov_b64 s[0:1], 0x1300
	s_mul_i32 s26, s26, s84
	v_lshl_add_u64 v[6:7], v[132:133], 0, s[0:1]
	s_mov_b32 s27, 1
	s_mov_b64 s[0:1], 0
	s_branch .LBB0_677
